# GEMM K-loops: LDS-DMA pieces in saddr form (per-tile 32-bit lane offsets against two wave-uniform bases advanced in SALU; no 64-bit VALU add per piece)
# speedup vs baseline: 1.0025x; 1.0025x over previous
.LBB0_41:
	s_nop 1
	v_sub_co_u32_e64 v0, s[16:17], s3, 64
	s_and_b64 s[16:17], s[16:17], exec
	v_readfirstlane_b32 s8, v0
	v_mov_b32_e32 v80, v220
	s_cselect_b32 s8, s3, s8
	s_cselect_b32 s10, 0, 8
	v_ashrrev_i32_e32 v16, 6, v80
	s_bfe_u32 s17, s8, 0x50003
	v_bfe_u32 v17, v80, 3, 3
	v_lshlrev_b32_e32 v18, 5, v16
	v_bfe_u32 v19, v80, 4, 2
	s_add_i32 s18, s8, s10
	s_lshl_b32 s8, s17, 7
	v_or_b32_e32 v1, v18, v17
	v_xor_b32_e32 v0, v19, v80
	v_add_u32_e32 v2, s8, v1
	s_movk_i32 s13, 0xb00
	v_lshlrev_b32_e32 v0, 3, v0
	s_lshl_b32 s19, s17, 13
	s_lshl_b32 s42, s18, 10
	v_mul_lo_u32 v2, v2, s13
	v_and_b32_e32 v20, 56, v0
	v_or_b32_e32 v3, 8, v1
	s_sub_i32 s10, s42, s19
	v_or_b32_e32 v192, v2, v20
	v_lshrrev_b32_e32 v2, 1, v3
	s_or_b32 s10, s10, s31
	v_xor_b32_e32 v2, v2, v80
	v_add_u32_e32 v4, s8, v3
	v_lshlrev_b32_e32 v2, 3, v2
	v_add_u32_e32 v3, s10, v3
	v_mul_lo_u32 v4, v4, s13
	v_and_b32_e32 v21, 56, v2
	v_mul_lo_u32 v3, v3, s13
	v_or_b32_e32 v2, v21, v4
	v_or_b32_e32 v4, v21, v3
	v_or_b32_e32 v3, 16, v1
	v_add_u32_e32 v5, s8, v3
	v_add_u32_e32 v3, s10, v3
	v_add_u32_e32 v0, s10, v1
	v_mul_lo_u32 v3, v3, s13
	v_or_b32_e32 v1, 24, v1
	v_or_b32_e32 v8, v3, v20
	v_lshrrev_b32_e32 v3, 1, v1
	v_mul_lo_u32 v5, v5, s13
	v_xor_b32_e32 v3, v3, v80
	v_or_b32_e32 v6, v5, v20
	v_add_u32_e32 v5, s8, v1
	v_lshlrev_b32_e32 v3, 3, v3
	v_add_u32_e32 v1, s10, v1
	s_cmp_lg_u32 32, -1
	v_and_b32_e32 v22, 56, v3
	v_mul_lo_u32 v1, v1, s13
	v_lshlrev_b32_e32 v23, 12, v16
	s_cselect_b32 s43, 32, 0
	v_ashrrev_i32_e32 v3, 1, v80
	v_or_b32_e32 v12, v22, v1
	v_add_u32_e32 v82, s43, v23
	v_and_b32_e32 v1, 15, v80
	v_and_b32_e32 v81, 0xffffffc0, v3
	s_add_i32 s44, s43, 0x4000
	v_mul_lo_u32 v0, v0, s13
	v_or_b32_e32 v24, v81, v1
	v_lshlrev_b32_e32 v1, 7, v80
	v_add_u32_e32 v3, s44, v23
	v_readfirstlane_b32 s44, v82
	v_readlane_b32 s88, v252, 11
	v_or_b32_e32 v0, v0, v20
	v_and_b32_e32 v83, 0x2780, v1
	v_lshl_add_u64 v[14:15], v[192:193], 1, s[28:29]
	s_mov_b32 m0, s44
	v_mov_b32_e32 v1, v193
	v_readlane_b32 s89, v252, 12
	v_readfirstlane_b32 s44, v3
	global_load_lds_dwordx4 v[14:15], off
	v_lshl_add_u64 v[0:1], v[0:1], 1, s[88:89]
	s_mov_b32 m0, s44
	v_mov_b32_e32 v3, v193
	s_add_i32 s44, s43, 0x400
	global_load_lds_dwordx4 v[0:1], off
	v_lshl_add_u64 v[0:1], v[2:3], 1, s[28:29]
	v_add_u32_e32 v2, s44, v23
	v_mul_lo_u32 v5, v5, s13
	v_readfirstlane_b32 s44, v2
	s_mov_b32 m0, s44
	s_add_i32 s44, s43, 0x4400
	v_add_u32_e32 v2, s44, v23
	global_load_lds_dwordx4 v[0:1], off
	v_readfirstlane_b32 s44, v2
	s_mov_b32 m0, s44
	s_add_i32 s44, s43, 0x800
	v_or_b32_e32 v10, v22, v5
	v_mov_b32_e32 v5, v193
	v_add_u32_e32 v2, s44, v23
	v_lshl_add_u64 v[0:1], v[4:5], 1, s[88:89]
	v_readfirstlane_b32 s44, v2
	global_load_lds_dwordx4 v[0:1], off
	s_mov_b32 m0, s44
	s_add_i32 s44, s43, 0x4800
	v_mov_b32_e32 v7, v193
	v_add_u32_e32 v2, s44, v23
	v_lshl_add_u64 v[0:1], v[6:7], 1, s[28:29]
	v_readfirstlane_b32 s44, v2
	global_load_lds_dwordx4 v[0:1], off
	s_mov_b32 m0, s44
	s_add_i32 s44, s43, 0xc00
	v_mov_b32_e32 v9, v193
	v_add_u32_e32 v2, s44, v23
	s_addk_i32 s43, 0x4c00
	v_lshl_add_u64 v[0:1], v[8:9], 1, s[88:89]
	v_mov_b32_e32 v11, v193
	v_readfirstlane_b32 s44, v2
	v_add_u32_e32 v2, s43, v23
	global_load_lds_dwordx4 v[0:1], off
	v_lshl_add_u64 v[0:1], v[10:11], 1, s[28:29]
	s_mov_b32 m0, s44
	v_mov_b32_e32 v13, v193
	v_readfirstlane_b32 s43, v2
	global_load_lds_dwordx4 v[0:1], off
	v_lshl_add_u64 v[0:1], v[12:13], 1, s[88:89]
	s_mov_b32 m0, s43
	s_mov_b32 s9, 0x16000
	global_load_lds_dwordx4 v[0:1], off
	v_bfe_u32 v0, v80, 1, 3
	v_xor_b32_e32 v1, v19, v0
	v_bitop3_b32 v0, v19, v0, 4 bitop3:0x36
	v_lshlrev_b32_e32 v84, 4, v0
	v_or_b32_e32 v0, s8, v17
	v_add_u32_e32 v0, v0, v18
	v_mul_lo_u32 v0, v0, s13
	v_lshlrev_b32_e32 v86, 4, v1
	v_or_b32_e32 v192, v0, v20
	s_mul_i32 s43, s17, 0x58000
	v_mul_lo_u32 v0, v16, s9
	v_mul_u32_u24_e32 v1, 0xb00, v17
	v_add3_u32 v2, v0, s43, v1
	v_or_b32_e32 v2, v2, v21
	s_add_i32 s44, s43, 0xb000
	v_lshl_add_u64 v[64:65], v[192:193], 1, s[40:41]
	v_add_u32_e32 v192, 0x5800, v2
	v_add3_u32 v2, s44, v0, v1
	s_add_i32 s43, s43, 0x10800
	v_lshl_add_u64 v[66:67], v[192:193], 1, s[40:41]
	v_or_b32_e32 v192, v2, v20
	v_add3_u32 v2, s43, v0, v1
	s_or_b32 s42, s42, s31
	v_lshl_add_u64 v[68:69], v[192:193], 1, s[40:41]
	v_or_b32_e32 v192, v2, v22
	v_add3_u32 v2, s42, v17, v18
	v_subrev_u32_e32 v2, s19, v2
	s_mul_i32 s18, s18, 0x2c0000
	v_readlane_b32 s9, v254, 28
	v_mul_lo_u32 v2, v2, s13
	s_add_i32 s19, s9, s18
	v_lshl_add_u64 v[70:71], v[192:193], 1, s[40:41]
	v_or_b32_e32 v192, v2, v20
	v_readlane_b32 s14, v254, 26
	v_add_u32_e32 v2, s19, v0
	v_readlane_b32 s9, v254, 29
	v_readlane_b32 s15, v254, 27
	v_add3_u32 v2, v2, v1, v21
	s_mul_i32 s17, s17, 0x1600000
	s_add_i32 s19, s9, s18
	v_readlane_b32 s9, v254, 30
	v_lshl_add_u64 v[72:73], v[192:193], 1, s[14:15]
	v_subrev_u32_e32 v192, s17, v2
	v_add_u32_e32 v2, s19, v0
	s_add_i32 s18, s9, s18
	v_add3_u32 v2, v2, v1, v20
	v_add_u32_e32 v0, s18, v0
	s_waitcnt vmcnt(0)
	v_lshl_add_u64 v[74:75], v[192:193], 1, s[14:15]
	v_subrev_u32_e32 v192, s17, v2
	v_add3_u32 v0, v0, v1, v22
	v_lshl_add_u64 v[76:77], v[192:193], 1, s[14:15]
	v_subrev_u32_e32 v192, s17, v0
	v_mov_b32_e32 v0, 0
	s_mov_b32 s16, 0
	v_lshlrev_b32_e32 v85, 7, v24
	v_lshl_add_u64 v[78:79], v[192:193], 1, s[14:15]
	s_mov_b64 s[42:43], 0
	v_mov_b32_e32 v1, v0
	v_mov_b32_e32 v2, v0
	v_mov_b32_e32 v3, v0
	v_mov_b32_e32 v4, v0
	v_mov_b32_e32 v5, v0
	v_mov_b32_e32 v6, v0
	v_mov_b32_e32 v7, v0
	v_mov_b32_e32 v8, v0
	v_mov_b32_e32 v9, v0
	v_mov_b32_e32 v10, v0
	v_mov_b32_e32 v11, v0
	v_mov_b32_e32 v12, v0
	v_mov_b32_e32 v13, v0
	v_mov_b32_e32 v14, v0
	v_mov_b32_e32 v15, v0
	v_mov_b32_e32 v16, v0
	v_mov_b32_e32 v17, v0
	v_mov_b32_e32 v18, v0
	v_mov_b32_e32 v19, v0
	v_mov_b32_e32 v20, v0
	v_mov_b32_e32 v21, v0
	v_mov_b32_e32 v22, v0
	v_mov_b32_e32 v23, v0
	v_mov_b32_e32 v24, v0
	v_mov_b32_e32 v25, v0
	v_mov_b32_e32 v26, v0
	v_mov_b32_e32 v27, v0
	v_mov_b32_e32 v28, v0
	v_mov_b32_e32 v29, v0
	v_mov_b32_e32 v30, v0
	v_mov_b32_e32 v31, v0
	v_mov_b32_e32 v32, v0
	v_mov_b32_e32 v33, v0
	v_mov_b32_e32 v34, v0
	v_mov_b32_e32 v35, v0
	v_mov_b32_e32 v36, v0
	v_mov_b32_e32 v37, v0
	v_mov_b32_e32 v38, v0
	v_mov_b32_e32 v39, v0
	v_mov_b32_e32 v40, v0
	v_mov_b32_e32 v41, v0
	v_mov_b32_e32 v42, v0
	v_mov_b32_e32 v43, v0
	v_mov_b32_e32 v44, v0
	v_mov_b32_e32 v45, v0
	v_mov_b32_e32 v46, v0
	v_mov_b32_e32 v47, v0
	v_mov_b32_e32 v48, v0
	v_mov_b32_e32 v49, v0
	v_mov_b32_e32 v50, v0
	v_mov_b32_e32 v51, v0
	v_mov_b32_e32 v52, v0
	v_mov_b32_e32 v53, v0
	v_mov_b32_e32 v54, v0
	v_mov_b32_e32 v55, v0
	v_mov_b32_e32 v56, v0
	v_mov_b32_e32 v57, v0
	v_mov_b32_e32 v58, v0
	v_mov_b32_e32 v59, v0
	v_mov_b32_e32 v60, v0
	v_mov_b32_e32 v61, v0
	v_mov_b32_e32 v62, v0
	v_mov_b32_e32 v63, v0
	v_readlane_b32 s90, v252, 13
	v_readlane_b32 s91, v252, 14
	v_readlane_b32 s92, v252, 15
	v_readlane_b32 s93, v252, 16
	v_readlane_b32 s94, v252, 17
	v_readlane_b32 s95, v252, 18
	s_waitcnt vmcnt(0) lgkmcnt(0)
	s_barrier
	v_add_u32_e32 v134, 32, v85
	v_add_u32_e32 v135, 32, v83
	v_add_u32_e32 v132, v134, v86
	v_add_u32_e32 v133, v135, v86
	ds_read_b128 v[88:91], v132
	ds_read_b128 v[96:99], v132 offset:2048
	ds_read_b128 v[104:107], v132 offset:4096
	ds_read_b128 v[112:115], v132 offset:6144
	ds_read_b128 v[92:95], v133 offset:16384
	ds_read_b128 v[100:103], v133 offset:18432
	ds_read_b128 v[108:111], v133 offset:20480
	ds_read_b128 v[116:119], v133 offset:22528
	v_readfirstlane_b32 s98, v64
	v_readfirstlane_b32 s99, v65
	v_readfirstlane_b32 s100, v72
	v_readfirstlane_b32 s101, v73
	s_sub_u32 s98, s98, 0x80
	s_subb_u32 s99, s99, 0
	s_sub_u32 s100, s100, 0x80
	s_subb_u32 s101, s101, 0
	v_subrev_u32_e32 v64, s98, v64
	v_subrev_u32_e32 v66, s98, v66
	v_subrev_u32_e32 v68, s98, v68
	v_subrev_u32_e32 v70, s98, v70
	v_subrev_u32_e32 v72, s100, v72
	v_subrev_u32_e32 v74, s100, v74
	v_subrev_u32_e32 v76, s100, v76
	v_subrev_u32_e32 v78, s100, v78
	v_add_u32_e32 v128, 0x8000, v82
	s_nop 0
	v_readfirstlane_b32 s18, v128
	s_nop 1
	s_mov_b32 m0, s18
	s_nop 0
	global_load_lds_dwordx4 v64, s[98:99]
	s_add_i32 m0, s18, 0x4000
	s_nop 0
	global_load_lds_dwordx4 v72, s[100:101]
	s_add_i32 m0, s18, 0x400
	s_nop 0
	global_load_lds_dwordx4 v66, s[98:99]
	s_add_i32 m0, s18, 0x4400
	s_nop 0
	global_load_lds_dwordx4 v74, s[100:101]
	s_add_i32 m0, s18, 0x800
	s_nop 0
	global_load_lds_dwordx4 v68, s[98:99]
	s_add_i32 m0, s18, 0x4800
	s_nop 0
	global_load_lds_dwordx4 v76, s[100:101]
	s_add_i32 m0, s18, 0xc00
	s_nop 0
	global_load_lds_dwordx4 v70, s[98:99]
	s_add_i32 m0, s18, 0x4c00
	s_nop 0
	global_load_lds_dwordx4 v78, s[100:101]
	s_add_u32 s42, s42, 0x80
	s_addc_u32 s43, s43, 0
	s_add_u32 s98, s98, 0x80
	s_addc_u32 s99, s99, 0
	s_add_u32 s100, s100, 0x80
	s_addc_u32 s101, s101, 0
.Lg42_loop:
	s_and_b32 s17, s16, 0x8000
	s_xor_b32 s18, s17, 0x8000
	v_add_u32_e32 v132, v134, v84
	v_add_u32_e32 v133, v135, v84
	ds_read_b128 v[152:155], v132
	ds_read_b128 v[156:159], v132 offset:2048
	ds_read_b128 v[160:163], v132 offset:4096
	ds_read_b128 v[164:167], v132 offset:6144
	s_waitcnt lgkmcnt(4)
	v_mfma_f32_16x16x32_bf16 v[60:63], v[88:91], v[92:95], v[60:63]
	v_mfma_f32_16x16x32_bf16 v[56:59], v[88:91], v[100:103], v[56:59]
	v_mfma_f32_16x16x32_bf16 v[52:55], v[88:91], v[108:111], v[52:55]
	v_mfma_f32_16x16x32_bf16 v[48:51], v[88:91], v[116:119], v[48:51]
	ds_read_b128 v[168:171], v133 offset:16384
	ds_read_b128 v[172:175], v133 offset:18432
	ds_read_b128 v[176:179], v133 offset:20480
	ds_read_b128 v[180:183], v133 offset:22528
	v_mfma_f32_16x16x32_bf16 v[44:47], v[96:99], v[92:95], v[44:47]
	v_mfma_f32_16x16x32_bf16 v[40:43], v[96:99], v[100:103], v[40:43]
	v_mfma_f32_16x16x32_bf16 v[36:39], v[96:99], v[108:111], v[36:39]
	v_mfma_f32_16x16x32_bf16 v[32:35], v[96:99], v[116:119], v[32:35]
	v_mfma_f32_16x16x32_bf16 v[28:31], v[104:107], v[92:95], v[28:31]
	v_mfma_f32_16x16x32_bf16 v[24:27], v[104:107], v[100:103], v[24:27]
	v_mfma_f32_16x16x32_bf16 v[20:23], v[104:107], v[108:111], v[20:23]
	v_mfma_f32_16x16x32_bf16 v[16:19], v[104:107], v[116:119], v[16:19]
	v_mfma_f32_16x16x32_bf16 v[12:15], v[112:115], v[92:95], v[12:15]
	v_mfma_f32_16x16x32_bf16 v[8:11], v[112:115], v[100:103], v[8:11]
	v_mfma_f32_16x16x32_bf16 v[4:7], v[112:115], v[108:111], v[4:7]
	v_mfma_f32_16x16x32_bf16 v[0:3], v[112:115], v[116:119], v[0:3]
	s_waitcnt vmcnt(0) lgkmcnt(0)
	s_barrier
	v_add_u32_e32 v128, s17, v82
	s_add_i32 s17, s18, 32
	v_add_u32_e32 v134, s17, v85
	v_add_u32_e32 v135, s17, v83
	v_add_u32_e32 v132, v134, v86
	v_add_u32_e32 v133, v135, v86
	ds_read_b128 v[88:91], v132
	ds_read_b128 v[96:99], v132 offset:2048
	ds_read_b128 v[104:107], v132 offset:4096
	ds_read_b128 v[112:115], v132 offset:6144
	ds_read_b128 v[92:95], v133 offset:16384
	ds_read_b128 v[100:103], v133 offset:18432
	ds_read_b128 v[108:111], v133 offset:20480
	ds_read_b128 v[116:119], v133 offset:22528
	v_readfirstlane_b32 s18, v128
	v_mfma_f32_16x16x32_bf16 v[60:63], v[152:155], v[168:171], v[60:63]
	s_mov_b32 m0, s18
	s_nop 0
	global_load_lds_dwordx4 v64, s[98:99]
	v_mfma_f32_16x16x32_bf16 v[56:59], v[152:155], v[172:175], v[56:59]
	v_mfma_f32_16x16x32_bf16 v[52:55], v[152:155], v[176:179], v[52:55]
	s_add_i32 m0, s18, 0x4000
	s_nop 0
	global_load_lds_dwordx4 v72, s[100:101]
	v_mfma_f32_16x16x32_bf16 v[48:51], v[152:155], v[180:183], v[48:51]
	v_mfma_f32_16x16x32_bf16 v[44:47], v[156:159], v[168:171], v[44:47]
	s_add_i32 m0, s18, 0x400
	s_nop 0
	global_load_lds_dwordx4 v66, s[98:99]
	v_mfma_f32_16x16x32_bf16 v[40:43], v[156:159], v[172:175], v[40:43]
	v_mfma_f32_16x16x32_bf16 v[36:39], v[156:159], v[176:179], v[36:39]
	s_add_i32 m0, s18, 0x4400
	s_nop 0
	global_load_lds_dwordx4 v74, s[100:101]
	v_mfma_f32_16x16x32_bf16 v[32:35], v[156:159], v[180:183], v[32:35]
	v_mfma_f32_16x16x32_bf16 v[28:31], v[160:163], v[168:171], v[28:31]
	s_add_i32 m0, s18, 0x800
	s_nop 0
	global_load_lds_dwordx4 v68, s[98:99]
	v_mfma_f32_16x16x32_bf16 v[24:27], v[160:163], v[172:175], v[24:27]
	v_mfma_f32_16x16x32_bf16 v[20:23], v[160:163], v[176:179], v[20:23]
	s_add_i32 m0, s18, 0x4800
	s_nop 0
	global_load_lds_dwordx4 v76, s[100:101]
	v_mfma_f32_16x16x32_bf16 v[16:19], v[160:163], v[180:183], v[16:19]
	v_mfma_f32_16x16x32_bf16 v[12:15], v[164:167], v[168:171], v[12:15]
	s_add_i32 m0, s18, 0xc00
	s_nop 0
	global_load_lds_dwordx4 v70, s[98:99]
	v_mfma_f32_16x16x32_bf16 v[8:11], v[164:167], v[172:175], v[8:11]
	v_mfma_f32_16x16x32_bf16 v[4:7], v[164:167], v[176:179], v[4:7]
	s_add_i32 m0, s18, 0x4c00
	s_nop 0
	global_load_lds_dwordx4 v78, s[100:101]
	v_mfma_f32_16x16x32_bf16 v[0:3], v[164:167], v[180:183], v[0:3]
	s_add_i32 s16, s16, 0x8000
	s_add_u32 s42, s42, 0x80
	s_addc_u32 s43, s43, 0
	s_add_u32 s98, s98, 0x80
	s_addc_u32 s99, s99, 0
	s_add_u32 s100, s100, 0x80
	s_addc_u32 s101, s101, 0
	s_cmpk_lg_i32 s42, 0x1580
	s_cbranch_scc1 .Lg42_loop
	s_and_b32 s17, s16, 0x8000
	s_xor_b32 s18, s17, 0x8000
	v_add_u32_e32 v132, v134, v84
	v_add_u32_e32 v133, v135, v84
	ds_read_b128 v[152:155], v132
	ds_read_b128 v[156:159], v132 offset:2048
	ds_read_b128 v[160:163], v132 offset:4096
	ds_read_b128 v[164:167], v132 offset:6144
	s_waitcnt lgkmcnt(4)
	v_mfma_f32_16x16x32_bf16 v[60:63], v[88:91], v[92:95], v[60:63]
	v_mfma_f32_16x16x32_bf16 v[56:59], v[88:91], v[100:103], v[56:59]
	v_mfma_f32_16x16x32_bf16 v[52:55], v[88:91], v[108:111], v[52:55]
	v_mfma_f32_16x16x32_bf16 v[48:51], v[88:91], v[116:119], v[48:51]
	ds_read_b128 v[168:171], v133 offset:16384
	ds_read_b128 v[172:175], v133 offset:18432
	ds_read_b128 v[176:179], v133 offset:20480
	ds_read_b128 v[180:183], v133 offset:22528
	v_mfma_f32_16x16x32_bf16 v[44:47], v[96:99], v[92:95], v[44:47]
	v_mfma_f32_16x16x32_bf16 v[40:43], v[96:99], v[100:103], v[40:43]
	v_mfma_f32_16x16x32_bf16 v[36:39], v[96:99], v[108:111], v[36:39]
	v_mfma_f32_16x16x32_bf16 v[32:35], v[96:99], v[116:119], v[32:35]
	v_mfma_f32_16x16x32_bf16 v[28:31], v[104:107], v[92:95], v[28:31]
	v_mfma_f32_16x16x32_bf16 v[24:27], v[104:107], v[100:103], v[24:27]
	v_mfma_f32_16x16x32_bf16 v[20:23], v[104:107], v[108:111], v[20:23]
	v_mfma_f32_16x16x32_bf16 v[16:19], v[104:107], v[116:119], v[16:19]
	v_mfma_f32_16x16x32_bf16 v[12:15], v[112:115], v[92:95], v[12:15]
	v_mfma_f32_16x16x32_bf16 v[8:11], v[112:115], v[100:103], v[8:11]
	v_mfma_f32_16x16x32_bf16 v[4:7], v[112:115], v[108:111], v[4:7]
	v_mfma_f32_16x16x32_bf16 v[0:3], v[112:115], v[116:119], v[0:3]
	s_waitcnt vmcnt(0) lgkmcnt(0)
	s_barrier
	v_mfma_f32_16x16x32_bf16 v[60:63], v[152:155], v[168:171], v[60:63]
	v_mfma_f32_16x16x32_bf16 v[56:59], v[152:155], v[172:175], v[56:59]
	v_mfma_f32_16x16x32_bf16 v[52:55], v[152:155], v[176:179], v[52:55]
	v_mfma_f32_16x16x32_bf16 v[48:51], v[152:155], v[180:183], v[48:51]
	v_mfma_f32_16x16x32_bf16 v[44:47], v[156:159], v[168:171], v[44:47]
	v_mfma_f32_16x16x32_bf16 v[40:43], v[156:159], v[172:175], v[40:43]
	v_mfma_f32_16x16x32_bf16 v[36:39], v[156:159], v[176:179], v[36:39]
	v_mfma_f32_16x16x32_bf16 v[32:35], v[156:159], v[180:183], v[32:35]
	v_mfma_f32_16x16x32_bf16 v[28:31], v[160:163], v[168:171], v[28:31]
	v_mfma_f32_16x16x32_bf16 v[24:27], v[160:163], v[172:175], v[24:27]
	v_mfma_f32_16x16x32_bf16 v[20:23], v[160:163], v[176:179], v[20:23]
	v_mfma_f32_16x16x32_bf16 v[16:19], v[160:163], v[180:183], v[16:19]
	v_mfma_f32_16x16x32_bf16 v[12:15], v[164:167], v[168:171], v[12:15]
	v_mfma_f32_16x16x32_bf16 v[8:11], v[164:167], v[172:175], v[8:11]
	v_mfma_f32_16x16x32_bf16 v[4:7], v[164:167], v[176:179], v[4:7]
	v_mfma_f32_16x16x32_bf16 v[0:3], v[164:167], v[180:183], v[0:3]
	v_add_u32_e32 v82, 32, v85
	v_add_u32_e32 v83, 32, v83
	v_add_u32_e32 v85, v82, v86
	ds_read_b128 v[64:67], v85 offset:32768
	v_add_u32_e32 v98, v83, v86
	ds_read_b128 v[72:75], v85 offset:34816
	ds_read_b128 v[86:89], v85 offset:36864
	ds_read_b128 v[94:97], v85 offset:38912
	ds_read_b128 v[90:93], v98 offset:53248
	ds_read_b128 v[68:71], v98 offset:49152
	ds_read_b128 v[76:79], v98 offset:51200
	ds_read_b128 v[98:101], v98 offset:55296
	s_waitcnt lgkmcnt(3)
	v_mfma_f32_16x16x32_bf16 v[52:55], v[64:67], v[90:93], v[52:55]
	s_add_i32 s3, s3, s2
	s_cmpk_gt_u32 s3, 0x7f
	v_mfma_f32_16x16x32_bf16 v[36:39], v[72:75], v[90:93], v[36:39]
	v_mfma_f32_16x16x32_bf16 v[20:23], v[86:89], v[90:93], v[20:23]
	v_mfma_f32_16x16x32_bf16 v[4:7], v[94:97], v[90:93], v[4:7]
	v_add_u32_e32 v90, v82, v84
	s_waitcnt lgkmcnt(2)
	v_mfma_f32_16x16x32_bf16 v[60:63], v[64:67], v[68:71], v[60:63]
	s_waitcnt lgkmcnt(1)
	v_mfma_f32_16x16x32_bf16 v[56:59], v[64:67], v[76:79], v[56:59]
	s_waitcnt lgkmcnt(0)
	v_mfma_f32_16x16x32_bf16 v[48:51], v[64:67], v[98:101], v[48:51]
	v_mfma_f32_16x16x32_bf16 v[44:47], v[72:75], v[68:71], v[44:47]
	v_mfma_f32_16x16x32_bf16 v[40:43], v[72:75], v[76:79], v[40:43]
	v_mfma_f32_16x16x32_bf16 v[32:35], v[72:75], v[98:101], v[32:35]
	v_mfma_f32_16x16x32_bf16 v[28:31], v[86:89], v[68:71], v[28:31]
	v_mfma_f32_16x16x32_bf16 v[24:27], v[86:89], v[76:79], v[24:27]
	v_mfma_f32_16x16x32_bf16 v[16:19], v[86:89], v[98:101], v[16:19]
	v_mfma_f32_16x16x32_bf16 v[12:15], v[94:97], v[68:71], v[12:15]
	v_mfma_f32_16x16x32_bf16 v[8:11], v[94:97], v[76:79], v[8:11]
	v_mfma_f32_16x16x32_bf16 v[0:3], v[94:97], v[98:101], v[0:3]
	ds_read_b128 v[64:67], v90 offset:32768
	v_add_u32_e32 v94, v83, v84
	ds_read_b128 v[72:75], v90 offset:34816
	ds_read_b128 v[82:85], v90 offset:36864
	ds_read_b128 v[90:93], v90 offset:38912
	ds_read_b128 v[68:71], v94 offset:49152
	ds_read_b128 v[76:79], v94 offset:51200
	ds_read_b128 v[86:89], v94 offset:53248
	ds_read_b128 v[94:97], v94 offset:55296
	s_waitcnt lgkmcnt(3)
	v_mfma_f32_16x16x32_bf16 v[60:63], v[64:67], v[68:71], v[60:63]
	s_waitcnt vmcnt(0)
	s_waitcnt lgkmcnt(0)
	s_barrier
	v_mfma_f32_16x16x32_bf16 v[56:59], v[64:67], v[76:79], v[56:59]
	s_nop 4
	v_cvt_pk_bf16_f32 v60, v60, v61
	v_cvt_pk_bf16_f32 v61, v62, v63
	v_mfma_f32_16x16x32_bf16 v[52:55], v[64:67], v[86:89], v[52:55]
	v_mfma_f32_16x16x32_bf16 v[48:51], v[64:67], v[94:97], v[48:51]
	v_and_b32_e32 v65, 0x4f, v80
	v_or_b32_e32 v66, s10, v65
	v_add_u32_e32 v64, s8, v81
	v_mfma_f32_16x16x32_bf16 v[12:15], v[90:93], v[68:71], v[12:15]
	v_ashrrev_i32_e32 v67, 31, v66
	v_ashrrev_i32_e32 v65, 31, v64
	v_lshlrev_b64 v[64:65], 1, v[64:65]
	v_mfma_f32_16x16x32_bf16 v[44:47], v[72:75], v[68:71], v[44:47]
	v_mfma_f32_16x16x32_bf16 v[28:31], v[82:85], v[68:71], v[28:31]
	v_lshlrev_b64 v[68:69], 11, v[66:67]
	v_lshl_add_u64 v[68:69], s[72:73], 0, v[68:69]
	v_lshrrev_b32_e32 v67, 1, v80
	v_lshl_add_u64 v[68:69], v[68:69], 0, v[64:65]
	v_and_b32_e32 v192, 24, v67
	v_lshl_add_u64 v[68:69], v[68:69], 0, v[192:193]
	v_cvt_pk_bf16_f32 v12, v12, v13
	v_cvt_pk_bf16_f32 v13, v14, v15
	global_store_dwordx2 v[68:69], v[12:13], off offset:96
	v_or_b32_e32 v12, 16, v66
	v_mfma_f32_16x16x32_bf16 v[8:11], v[90:93], v[76:79], v[8:11]
	v_ashrrev_i32_e32 v13, 31, v12
	v_lshlrev_b64 v[12:13], 11, v[12:13]
	v_lshl_add_u64 v[12:13], s[72:73], 0, v[12:13]
	v_lshl_add_u64 v[12:13], v[12:13], 0, v[64:65]
	v_lshl_add_u64 v[12:13], v[12:13], 0, v[192:193]
	s_nop 2
	v_cvt_pk_bf16_f32 v8, v8, v9
	v_cvt_pk_bf16_f32 v9, v10, v11
	global_store_dwordx2 v[12:13], v[8:9], off offset:96
	v_or_b32_e32 v8, 32, v66
	v_mfma_f32_16x16x32_bf16 v[4:7], v[90:93], v[86:89], v[4:7]
	v_ashrrev_i32_e32 v9, 31, v8
	v_lshlrev_b64 v[8:9], 11, v[8:9]
	v_lshl_add_u64 v[8:9], s[72:73], 0, v[8:9]
	v_lshl_add_u64 v[8:9], v[8:9], 0, v[64:65]
	v_lshl_add_u64 v[8:9], v[8:9], 0, v[192:193]
	s_nop 2
	v_cvt_pk_bf16_f32 v4, v4, v5
	v_cvt_pk_bf16_f32 v5, v6, v7
	global_store_dwordx2 v[8:9], v[4:5], off offset:96
	v_or_b32_e32 v4, 48, v66
	v_ashrrev_i32_e32 v5, 31, v4
	v_mfma_f32_16x16x32_bf16 v[40:43], v[72:75], v[76:79], v[40:43]
	v_lshlrev_b64 v[4:5], 11, v[4:5]
	v_lshl_add_u64 v[4:5], s[72:73], 0, v[4:5]
	v_lshl_add_u64 v[4:5], v[4:5], 0, v[64:65]
	v_mfma_f32_16x16x32_bf16 v[36:39], v[72:75], v[86:89], v[36:39]
	v_cvt_pk_bf16_f32 v14, v56, v57
	v_cvt_pk_bf16_f32 v15, v58, v59
	v_cvt_pk_bf16_f32 v10, v52, v53
	v_mfma_f32_16x16x32_bf16 v[32:35], v[72:75], v[94:97], v[32:35]
	v_cvt_pk_bf16_f32 v11, v54, v55
	v_lshl_add_u64 v[4:5], v[4:5], 0, v[192:193]
	v_cvt_pk_bf16_f32 v6, v48, v49
	v_mfma_f32_16x16x32_bf16 v[24:27], v[82:85], v[76:79], v[24:27]
	v_cvt_pk_bf16_f32 v7, v50, v51
	global_store_dwordx2 v[12:13], v[14:15], off
	v_cvt_pk_bf16_f32 v14, v40, v41
	v_mfma_f32_16x16x32_bf16 v[20:23], v[82:85], v[86:89], v[20:23]
	v_cvt_pk_bf16_f32 v15, v42, v43
	global_store_dwordx2 v[8:9], v[10:11], off
	v_cvt_pk_bf16_f32 v10, v36, v37
	v_mfma_f32_16x16x32_bf16 v[16:19], v[82:85], v[94:97], v[16:19]
	v_cvt_pk_bf16_f32 v11, v38, v39
	global_store_dwordx2 v[4:5], v[6:7], off
	v_cvt_pk_bf16_f32 v6, v32, v33
	v_mfma_f32_16x16x32_bf16 v[0:3], v[90:93], v[94:97], v[0:3]
	v_cvt_pk_bf16_f32 v7, v34, v35
	v_cvt_pk_bf16_f32 v44, v44, v45
	v_cvt_pk_bf16_f32 v45, v46, v47
	v_cvt_pk_bf16_f32 v28, v28, v29
	v_cvt_pk_bf16_f32 v29, v30, v31
	global_store_dwordx2 v[12:13], v[14:15], off offset:32
	v_cvt_pk_bf16_f32 v14, v24, v25
	v_cvt_pk_bf16_f32 v15, v26, v27
	global_store_dwordx2 v[8:9], v[10:11], off offset:32
	v_cvt_pk_bf16_f32 v10, v20, v21
	v_cvt_pk_bf16_f32 v11, v22, v23
	global_store_dwordx2 v[4:5], v[6:7], off offset:32
	v_cvt_pk_bf16_f32 v6, v16, v17
	v_cvt_pk_bf16_f32 v7, v18, v19
	v_cvt_pk_bf16_f32 v0, v0, v1
	v_cvt_pk_bf16_f32 v1, v2, v3
	global_store_dwordx2 v[68:69], v[60:61], off
	global_store_dwordx2 v[68:69], v[44:45], off offset:32
	global_store_dwordx2 v[68:69], v[28:29], off offset:64
	global_store_dwordx2 v[12:13], v[14:15], off offset:64
	global_store_dwordx2 v[8:9], v[10:11], off offset:64
	global_store_dwordx2 v[4:5], v[6:7], off offset:64
	global_store_dwordx2 v[4:5], v[0:1], off offset:96
	s_cbranch_scc0 .LBB0_41

.LBB0_63:
	s_min_i32 s8, s12, 8
	s_mul_i32 s42, s8, 44
	s_mov_b32 s19, s16
	s_add_i32 s18, s18, 8
	s_add_i32 s12, s12, -8
	s_add_i32 s17, s17, -8
	s_sub_i32 s16, s16, s42
	s_cmp_ge_i32 s19, s42
	s_cbranch_scc1 .LBB0_63
	s_lshl_b32 s12, s8, 3
	s_abs_i32 s16, s12
	v_cvt_f32_u32_e32 v0, s16
	s_sub_i32 s44, 0, s16
	s_abs_i32 s43, s19
	s_xor_b32 s42, s19, s12
	v_rcp_iflag_f32_e32 v0, v0
	s_ashr_i32 s42, s42, 31
	v_mov_b32_e32 v80, v220
	v_mul_f32_e32 v0, 0x4f7ffffe, v0
	v_cvt_u32_f32_e32 v0, v0
	v_ashrrev_i32_e32 v16, 6, v80
	v_bfe_u32 v19, v80, 4, 2
	v_bfe_u32 v17, v80, 3, 3
	v_readfirstlane_b32 s45, v0
	s_mul_i32 s44, s44, s45
	s_mul_hi_u32 s44, s45, s44
	s_add_i32 s45, s45, s44
	s_mul_hi_u32 s44, s43, s45
	s_mul_i32 s45, s44, s16
	s_sub_i32 s43, s43, s45
	s_add_i32 s46, s44, 1
	s_sub_i32 s45, s43, s16
	s_cmp_ge_u32 s43, s16
	s_cselect_b32 s44, s46, s44
	s_cselect_b32 s43, s45, s43
	s_add_i32 s45, s44, 1
	s_cmp_ge_u32 s43, s16
	s_cselect_b32 s43, s45, s44
	s_abs_i32 s44, s8
	v_cvt_f32_u32_e32 v0, s44
	s_xor_b32 s43, s43, s42
	s_sub_i32 s45, 0, s44
	s_sub_i32 s46, s43, s42
	v_rcp_iflag_f32_e32 v0, v0
	s_mul_i32 s12, s46, s12
	s_sub_i32 s12, s19, s12
	s_abs_i32 s48, s12
	v_mul_f32_e32 v0, 0x4f7ffffe, v0
	v_cvt_u32_f32_e32 v0, v0
	s_xor_b32 s47, s12, s8
	s_ashr_i32 s47, s47, 31
	v_lshlrev_b32_e32 v18, 5, v16
	v_readfirstlane_b32 s49, v0
	s_mul_i32 s45, s45, s49
	s_mul_hi_u32 s45, s49, s45
	s_add_i32 s49, s49, s45
	s_mul_hi_u32 s45, s48, s49
	s_mul_i32 s49, s45, s44
	s_sub_i32 s48, s48, s49
	s_add_i32 s50, s45, 1
	s_sub_i32 s49, s48, s44
	s_cmp_ge_u32 s48, s44
	s_cselect_b32 s45, s50, s45
	s_cselect_b32 s48, s49, s48
	s_add_i32 s49, s45, 1
	s_cmp_ge_u32 s48, s44
	s_cselect_b32 s44, s49, s45
	s_xor_b32 s44, s44, s47
	s_sub_i32 s45, s44, s47
	s_mul_i32 s8, s45, s8
	s_add_i32 s12, s12, s18
	s_sub_i32 s12, s12, s8
	s_lshl_b32 s8, s46, 10
	s_lshl_b32 s45, s45, 7
	v_xor_b32_e32 v0, v19, v80
	s_add_i32 s8, s45, s8
	v_or_b32_e32 v1, v18, v17
	v_lshlrev_b32_e32 v0, 3, v0
	v_add_u32_e32 v2, s8, v1
	v_and_b32_e32 v20, 56, v0
	v_or_b32_e32 v3, 8, v1
	v_lshl_or_b32 v192, v2, 10, v20
	v_lshrrev_b32_e32 v2, 1, v3
	s_lshl_b32 s12, s12, 10
	v_readlane_b32 s9, v252, 39
	v_xor_b32_e32 v2, v2, v80
	s_or_b32 s12, s12, s9
	v_lshlrev_b32_e32 v2, 3, v2
	v_add_u32_e32 v4, s8, v3
	v_and_b32_e32 v21, 56, v2
	v_add_u32_e32 v3, s12, v3
	v_lshl_or_b32 v2, v4, 10, v21
	v_lshl_or_b32 v4, v3, 10, v21
	v_or_b32_e32 v3, 16, v1
	v_add_u32_e32 v0, s12, v1
	v_add_u32_e32 v5, s8, v3
	v_add_u32_e32 v3, s12, v3
	v_or_b32_e32 v1, 24, v1
	v_lshl_or_b32 v8, v3, 10, v20
	v_lshrrev_b32_e32 v3, 1, v1
	v_xor_b32_e32 v3, v3, v80
	s_cmp_lg_u32 32, -1
	v_lshlrev_b32_e32 v3, 3, v3
	v_lshlrev_b32_e32 v23, 12, v16
	s_cselect_b32 s45, 32, 0
	v_lshl_or_b32 v6, v5, 10, v20
	v_add_u32_e32 v5, s8, v1
	v_and_b32_e32 v22, 56, v3
	v_add_u32_e32 v1, s12, v1
	v_add_u32_e32 v82, s45, v23
	v_ashrrev_i32_e32 v3, 1, v80
	s_add_i32 s46, s45, 0x4000
	v_lshl_or_b32 v12, v1, 10, v22
	v_and_b32_e32 v1, 15, v80
	v_and_b32_e32 v81, 0xffffffc0, v3
	v_add_u32_e32 v3, s46, v23
	v_readfirstlane_b32 s46, v82
	v_lshl_or_b32 v0, v0, 10, v20
	v_or_b32_e32 v24, v81, v1
	v_lshl_add_u64 v[14:15], v[192:193], 1, s[28:29]
	s_mov_b32 m0, s46
	v_mov_b32_e32 v1, v193
	v_readfirstlane_b32 s46, v3
	global_load_lds_dwordx4 v[14:15], off
	v_lshl_add_u64 v[0:1], v[0:1], 1, s[74:75]
	s_mov_b32 m0, s46
	v_mov_b32_e32 v3, v193
	s_add_i32 s46, s45, 0x400
	global_load_lds_dwordx4 v[0:1], off
	v_lshl_add_u64 v[0:1], v[2:3], 1, s[28:29]
	v_add_u32_e32 v2, s46, v23
	v_lshl_or_b32 v10, v5, 10, v22
	v_readfirstlane_b32 s46, v2
	s_mov_b32 m0, s46
	s_add_i32 s46, s45, 0x4400
	v_add_u32_e32 v2, s46, v23
	global_load_lds_dwordx4 v[0:1], off
	v_readfirstlane_b32 s46, v2
	s_mov_b32 m0, s46
	s_add_i32 s46, s45, 0x800
	v_mov_b32_e32 v5, v193
	v_add_u32_e32 v2, s46, v23
	v_lshl_add_u64 v[0:1], v[4:5], 1, s[74:75]
	v_readfirstlane_b32 s46, v2
	global_load_lds_dwordx4 v[0:1], off
	s_mov_b32 m0, s46
	s_add_i32 s46, s45, 0x4800
	v_mov_b32_e32 v7, v193
	v_add_u32_e32 v2, s46, v23
	v_lshl_add_u64 v[0:1], v[6:7], 1, s[28:29]
	v_readfirstlane_b32 s46, v2
	global_load_lds_dwordx4 v[0:1], off
	s_mov_b32 m0, s46
	s_add_i32 s46, s45, 0xc00
	v_mov_b32_e32 v9, v193
	v_add_u32_e32 v2, s46, v23
	s_addk_i32 s45, 0x4c00
	v_lshl_add_u64 v[0:1], v[8:9], 1, s[74:75]
	v_mov_b32_e32 v11, v193
	v_readfirstlane_b32 s46, v2
	v_add_u32_e32 v2, s45, v23
	global_load_lds_dwordx4 v[0:1], off
	v_lshl_add_u64 v[0:1], v[10:11], 1, s[28:29]
	s_mov_b32 m0, s46
	v_mov_b32_e32 v13, v193
	v_readfirstlane_b32 s45, v2
	global_load_lds_dwordx4 v[0:1], off
	v_lshl_add_u64 v[0:1], v[12:13], 1, s[74:75]
	s_mov_b32 m0, s45
	s_lshl_b32 s45, s43, 10
	global_load_lds_dwordx4 v[0:1], off
	v_bfe_u32 v0, v80, 1, 3
	s_lshl_b32 s46, s44, 7
	v_xor_b32_e32 v1, v19, v0
	v_bitop3_b32 v0, v19, v0, 4 bitop3:0x36
	s_add_i32 s46, s46, s45
	v_lshlrev_b32_e32 v83, 4, v0
	v_or_b32_e32 v0, s46, v17
	v_add_u32_e32 v0, v0, v18
	s_lshl_b32 s45, s47, 7
	v_subrev_u32_e32 v0, s45, v0
	s_lshl_b32 s45, s42, 10
	v_subrev_u32_e32 v0, s45, v0
	s_lshl_b32 s45, s43, 20
	s_lshl_b32 s46, s44, 17
	v_lshl_or_b32 v192, v0, 10, v20
	v_lshlrev_b32_e32 v0, 15, v16
	s_add_i32 s45, s45, s46
	v_lshlrev_b32_e32 v84, 4, v1
	v_lshlrev_b32_e32 v1, 10, v17
	v_add_u32_e32 v2, s45, v0
	v_or_b32_e32 v2, v2, v1
	s_add_i32 s18, s19, s18
	s_lshl_b32 s19, s42, 3
	v_or3_b32 v3, v2, v21, s33
	s_lshl_b32 s45, s47, 17
	s_add_i32 s47, s47, s19
	v_subrev_u32_e32 v3, s45, v3
	s_lshl_b32 s46, s42, 20
	s_sub_i32 s19, s47, s44
	s_lshl_b32 s42, s43, 3
	v_lshl_add_u64 v[64:65], v[192:193], 1, s[40:41]
	v_subrev_u32_e32 v192, s46, v3
	v_or3_b32 v3, v2, v20, s68
	s_sub_i32 s19, s19, s42
	s_min_i32 s17, s17, 8
	v_subrev_u32_e32 v3, s45, v3
	v_or3_b32 v2, v2, v22, s67
	s_mul_i32 s19, s19, s17
	v_lshl_add_u64 v[66:67], v[192:193], 1, s[40:41]
	v_subrev_u32_e32 v192, s46, v3
	v_subrev_u32_e32 v2, s45, v2
	s_add_i32 s18, s18, s19
	v_lshl_add_u64 v[68:69], v[192:193], 1, s[40:41]
	v_subrev_u32_e32 v192, s46, v2
	v_add_u32_e32 v2, s31, v17
	s_lshl_b32 s17, s18, 10
	v_add3_u32 v2, v2, v18, s17
	v_lshl_add_u64 v[70:71], v[192:193], 1, s[40:41]
	v_lshl_or_b32 v192, v2, 10, v20
	v_add3_u32 v2, s58, v0, v1
	s_lshl_b32 s17, s18, 20
	v_lshl_add_u64 v[72:73], v[192:193], 1, s[56:57]
	v_add3_u32 v192, v2, v21, s17
	v_add3_u32 v2, s59, v0, v1
	v_readlane_b32 s9, v254, 34
	s_waitcnt vmcnt(0)
	v_lshl_add_u64 v[74:75], v[192:193], 1, s[56:57]
	v_add3_u32 v192, v2, v20, s17
	v_add3_u32 v0, s9, v0, v1
	v_lshlrev_b32_e32 v25, 7, v80
	v_lshl_add_u64 v[76:77], v[192:193], 1, s[56:57]
	v_add3_u32 v192, v0, v22, s17
	v_mov_b32_e32 v0, 0
	s_mov_b32 s16, 0
	v_lshlrev_b32_e32 v85, 7, v24
	v_and_b32_e32 v86, 0x2780, v25
	v_lshl_add_u64 v[78:79], v[192:193], 1, s[56:57]
	s_mov_b64 s[42:43], 0
	v_mov_b32_e32 v1, v0
	v_mov_b32_e32 v2, v0
	v_mov_b32_e32 v3, v0
	v_mov_b32_e32 v4, v0
	v_mov_b32_e32 v5, v0
	v_mov_b32_e32 v6, v0
	v_mov_b32_e32 v7, v0
	v_mov_b32_e32 v8, v0
	v_mov_b32_e32 v9, v0
	v_mov_b32_e32 v10, v0
	v_mov_b32_e32 v11, v0
	v_mov_b32_e32 v12, v0
	v_mov_b32_e32 v13, v0
	v_mov_b32_e32 v14, v0
	v_mov_b32_e32 v15, v0
	v_mov_b32_e32 v16, v0
	v_mov_b32_e32 v17, v0
	v_mov_b32_e32 v18, v0
	v_mov_b32_e32 v19, v0
	v_mov_b32_e32 v20, v0
	v_mov_b32_e32 v21, v0
	v_mov_b32_e32 v22, v0
	v_mov_b32_e32 v23, v0
	v_mov_b32_e32 v24, v0
	v_mov_b32_e32 v25, v0
	v_mov_b32_e32 v26, v0
	v_mov_b32_e32 v27, v0
	v_mov_b32_e32 v28, v0
	v_mov_b32_e32 v29, v0
	v_mov_b32_e32 v30, v0
	v_mov_b32_e32 v31, v0
	v_mov_b32_e32 v32, v0
	v_mov_b32_e32 v33, v0
	v_mov_b32_e32 v34, v0
	v_mov_b32_e32 v35, v0
	v_mov_b32_e32 v36, v0
	v_mov_b32_e32 v37, v0
	v_mov_b32_e32 v38, v0
	v_mov_b32_e32 v39, v0
	v_mov_b32_e32 v40, v0
	v_mov_b32_e32 v41, v0
	v_mov_b32_e32 v42, v0
	v_mov_b32_e32 v43, v0
	v_mov_b32_e32 v44, v0
	v_mov_b32_e32 v45, v0
	v_mov_b32_e32 v46, v0
	v_mov_b32_e32 v47, v0
	v_mov_b32_e32 v48, v0
	v_mov_b32_e32 v49, v0
	v_mov_b32_e32 v50, v0
	v_mov_b32_e32 v51, v0
	v_mov_b32_e32 v52, v0
	v_mov_b32_e32 v53, v0
	v_mov_b32_e32 v54, v0
	v_mov_b32_e32 v55, v0
	v_mov_b32_e32 v56, v0
	v_mov_b32_e32 v57, v0
	v_mov_b32_e32 v58, v0
	v_mov_b32_e32 v59, v0
	v_mov_b32_e32 v60, v0
	v_mov_b32_e32 v61, v0
	v_mov_b32_e32 v62, v0
	v_mov_b32_e32 v63, v0
	s_waitcnt vmcnt(0) lgkmcnt(0)
	s_barrier
	v_add_u32_e32 v134, 32, v85
	v_add_u32_e32 v135, 32, v86
	v_add_u32_e32 v132, v134, v84
	v_add_u32_e32 v133, v135, v84
	ds_read_b128 v[88:91], v132
	ds_read_b128 v[96:99], v132 offset:2048
	ds_read_b128 v[104:107], v132 offset:4096
	ds_read_b128 v[112:115], v132 offset:6144
	ds_read_b128 v[92:95], v133 offset:16384
	ds_read_b128 v[100:103], v133 offset:18432
	ds_read_b128 v[108:111], v133 offset:20480
	ds_read_b128 v[116:119], v133 offset:22528
	v_readfirstlane_b32 s98, v64
	v_readfirstlane_b32 s99, v65
	v_readfirstlane_b32 s100, v72
	v_readfirstlane_b32 s101, v73
	s_sub_u32 s98, s98, 0x80
	s_subb_u32 s99, s99, 0
	s_sub_u32 s100, s100, 0x80
	s_subb_u32 s101, s101, 0
	v_subrev_u32_e32 v64, s98, v64
	v_subrev_u32_e32 v66, s98, v66
	v_subrev_u32_e32 v68, s98, v68
	v_subrev_u32_e32 v70, s98, v70
	v_subrev_u32_e32 v72, s100, v72
	v_subrev_u32_e32 v74, s100, v74
	v_subrev_u32_e32 v76, s100, v76
	v_subrev_u32_e32 v78, s100, v78
	v_add_u32_e32 v128, 0x8000, v82
	s_nop 0
	v_readfirstlane_b32 s18, v128
	s_nop 1
	s_mov_b32 m0, s18
	s_nop 0
	global_load_lds_dwordx4 v64, s[98:99]
	s_add_i32 m0, s18, 0x4000
	s_nop 0
	global_load_lds_dwordx4 v72, s[100:101]
	s_add_i32 m0, s18, 0x400
	s_nop 0
	global_load_lds_dwordx4 v66, s[98:99]
	s_add_i32 m0, s18, 0x4400
	s_nop 0
	global_load_lds_dwordx4 v74, s[100:101]
	s_add_i32 m0, s18, 0x800
	s_nop 0
	global_load_lds_dwordx4 v68, s[98:99]
	s_add_i32 m0, s18, 0x4800
	s_nop 0
	global_load_lds_dwordx4 v76, s[100:101]
	s_add_i32 m0, s18, 0xc00
	s_nop 0
	global_load_lds_dwordx4 v70, s[98:99]
	s_add_i32 m0, s18, 0x4c00
	s_nop 0
	global_load_lds_dwordx4 v78, s[100:101]
	s_add_u32 s42, s42, 0x80
	s_addc_u32 s43, s43, 0
	s_add_u32 s98, s98, 0x80
	s_addc_u32 s99, s99, 0
	s_add_u32 s100, s100, 0x80
	s_addc_u32 s101, s101, 0
.Lg65_loop:
	s_and_b32 s17, s16, 0x8000
	s_xor_b32 s18, s17, 0x8000
	v_add_u32_e32 v132, v134, v83
	v_add_u32_e32 v133, v135, v83
	ds_read_b128 v[152:155], v132
	ds_read_b128 v[156:159], v132 offset:2048
	ds_read_b128 v[160:163], v132 offset:4096
	ds_read_b128 v[164:167], v132 offset:6144
	s_waitcnt lgkmcnt(4)
	v_mfma_f32_16x16x32_bf16 v[60:63], v[88:91], v[92:95], v[60:63]
	v_mfma_f32_16x16x32_bf16 v[56:59], v[88:91], v[100:103], v[56:59]
	v_mfma_f32_16x16x32_bf16 v[52:55], v[88:91], v[108:111], v[52:55]
	v_mfma_f32_16x16x32_bf16 v[48:51], v[88:91], v[116:119], v[48:51]
	ds_read_b128 v[168:171], v133 offset:16384
	ds_read_b128 v[172:175], v133 offset:18432
	ds_read_b128 v[176:179], v133 offset:20480
	ds_read_b128 v[180:183], v133 offset:22528
	v_mfma_f32_16x16x32_bf16 v[44:47], v[96:99], v[92:95], v[44:47]
	v_mfma_f32_16x16x32_bf16 v[40:43], v[96:99], v[100:103], v[40:43]
	v_mfma_f32_16x16x32_bf16 v[36:39], v[96:99], v[108:111], v[36:39]
	v_mfma_f32_16x16x32_bf16 v[32:35], v[96:99], v[116:119], v[32:35]
	v_mfma_f32_16x16x32_bf16 v[28:31], v[104:107], v[92:95], v[28:31]
	v_mfma_f32_16x16x32_bf16 v[24:27], v[104:107], v[100:103], v[24:27]
	v_mfma_f32_16x16x32_bf16 v[20:23], v[104:107], v[108:111], v[20:23]
	v_mfma_f32_16x16x32_bf16 v[16:19], v[104:107], v[116:119], v[16:19]
	v_mfma_f32_16x16x32_bf16 v[12:15], v[112:115], v[92:95], v[12:15]
	v_mfma_f32_16x16x32_bf16 v[8:11], v[112:115], v[100:103], v[8:11]
	v_mfma_f32_16x16x32_bf16 v[4:7], v[112:115], v[108:111], v[4:7]
	v_mfma_f32_16x16x32_bf16 v[0:3], v[112:115], v[116:119], v[0:3]
	s_waitcnt vmcnt(0) lgkmcnt(0)
	s_barrier
	v_add_u32_e32 v128, s17, v82
	s_add_i32 s17, s18, 32
	v_add_u32_e32 v134, s17, v85
	v_add_u32_e32 v135, s17, v86
	v_add_u32_e32 v132, v134, v84
	v_add_u32_e32 v133, v135, v84
	ds_read_b128 v[88:91], v132
	ds_read_b128 v[96:99], v132 offset:2048
	ds_read_b128 v[104:107], v132 offset:4096
	ds_read_b128 v[112:115], v132 offset:6144
	ds_read_b128 v[92:95], v133 offset:16384
	ds_read_b128 v[100:103], v133 offset:18432
	ds_read_b128 v[108:111], v133 offset:20480
	ds_read_b128 v[116:119], v133 offset:22528
	v_readfirstlane_b32 s18, v128
	v_mfma_f32_16x16x32_bf16 v[60:63], v[152:155], v[168:171], v[60:63]
	s_mov_b32 m0, s18
	s_nop 0
	global_load_lds_dwordx4 v64, s[98:99]
	v_mfma_f32_16x16x32_bf16 v[56:59], v[152:155], v[172:175], v[56:59]
	v_mfma_f32_16x16x32_bf16 v[52:55], v[152:155], v[176:179], v[52:55]
	s_add_i32 m0, s18, 0x4000
	s_nop 0
	global_load_lds_dwordx4 v72, s[100:101]
	v_mfma_f32_16x16x32_bf16 v[48:51], v[152:155], v[180:183], v[48:51]
	v_mfma_f32_16x16x32_bf16 v[44:47], v[156:159], v[168:171], v[44:47]
	s_add_i32 m0, s18, 0x400
	s_nop 0
	global_load_lds_dwordx4 v66, s[98:99]
	v_mfma_f32_16x16x32_bf16 v[40:43], v[156:159], v[172:175], v[40:43]
	v_mfma_f32_16x16x32_bf16 v[36:39], v[156:159], v[176:179], v[36:39]
	s_add_i32 m0, s18, 0x4400
	s_nop 0
	global_load_lds_dwordx4 v74, s[100:101]
	v_mfma_f32_16x16x32_bf16 v[32:35], v[156:159], v[180:183], v[32:35]
	v_mfma_f32_16x16x32_bf16 v[28:31], v[160:163], v[168:171], v[28:31]
	s_add_i32 m0, s18, 0x800
	s_nop 0
	global_load_lds_dwordx4 v68, s[98:99]
	v_mfma_f32_16x16x32_bf16 v[24:27], v[160:163], v[172:175], v[24:27]
	v_mfma_f32_16x16x32_bf16 v[20:23], v[160:163], v[176:179], v[20:23]
	s_add_i32 m0, s18, 0x4800
	s_nop 0
	global_load_lds_dwordx4 v76, s[100:101]
	v_mfma_f32_16x16x32_bf16 v[16:19], v[160:163], v[180:183], v[16:19]
	v_mfma_f32_16x16x32_bf16 v[12:15], v[164:167], v[168:171], v[12:15]
	s_add_i32 m0, s18, 0xc00
	s_nop 0
	global_load_lds_dwordx4 v70, s[98:99]
	v_mfma_f32_16x16x32_bf16 v[8:11], v[164:167], v[172:175], v[8:11]
	v_mfma_f32_16x16x32_bf16 v[4:7], v[164:167], v[176:179], v[4:7]
	s_add_i32 m0, s18, 0x4c00
	s_nop 0
	global_load_lds_dwordx4 v78, s[100:101]
	v_mfma_f32_16x16x32_bf16 v[0:3], v[164:167], v[180:183], v[0:3]
	s_add_i32 s16, s16, 0x8000
	s_add_u32 s42, s42, 0x80
	s_addc_u32 s43, s43, 0
	s_add_u32 s98, s98, 0x80
	s_addc_u32 s99, s99, 0
	s_add_u32 s100, s100, 0x80
	s_addc_u32 s101, s101, 0
	s_cmpk_lg_i32 s42, 0x780
	s_cbranch_scc1 .Lg65_loop
	s_and_b32 s17, s16, 0x8000
	s_xor_b32 s18, s17, 0x8000
	v_add_u32_e32 v132, v134, v83
	v_add_u32_e32 v133, v135, v83
	ds_read_b128 v[152:155], v132
	ds_read_b128 v[156:159], v132 offset:2048
	ds_read_b128 v[160:163], v132 offset:4096
	ds_read_b128 v[164:167], v132 offset:6144
	s_waitcnt lgkmcnt(4)
	v_mfma_f32_16x16x32_bf16 v[60:63], v[88:91], v[92:95], v[60:63]
	v_mfma_f32_16x16x32_bf16 v[56:59], v[88:91], v[100:103], v[56:59]
	v_mfma_f32_16x16x32_bf16 v[52:55], v[88:91], v[108:111], v[52:55]
	v_mfma_f32_16x16x32_bf16 v[48:51], v[88:91], v[116:119], v[48:51]
	ds_read_b128 v[168:171], v133 offset:16384
	ds_read_b128 v[172:175], v133 offset:18432
	ds_read_b128 v[176:179], v133 offset:20480
	ds_read_b128 v[180:183], v133 offset:22528
	v_mfma_f32_16x16x32_bf16 v[44:47], v[96:99], v[92:95], v[44:47]
	v_mfma_f32_16x16x32_bf16 v[40:43], v[96:99], v[100:103], v[40:43]
	v_mfma_f32_16x16x32_bf16 v[36:39], v[96:99], v[108:111], v[36:39]
	v_mfma_f32_16x16x32_bf16 v[32:35], v[96:99], v[116:119], v[32:35]
	v_mfma_f32_16x16x32_bf16 v[28:31], v[104:107], v[92:95], v[28:31]
	v_mfma_f32_16x16x32_bf16 v[24:27], v[104:107], v[100:103], v[24:27]
	v_mfma_f32_16x16x32_bf16 v[20:23], v[104:107], v[108:111], v[20:23]
	v_mfma_f32_16x16x32_bf16 v[16:19], v[104:107], v[116:119], v[16:19]
	v_mfma_f32_16x16x32_bf16 v[12:15], v[112:115], v[92:95], v[12:15]
	v_mfma_f32_16x16x32_bf16 v[8:11], v[112:115], v[100:103], v[8:11]
	v_mfma_f32_16x16x32_bf16 v[4:7], v[112:115], v[108:111], v[4:7]
	v_mfma_f32_16x16x32_bf16 v[0:3], v[112:115], v[116:119], v[0:3]
	s_waitcnt vmcnt(0) lgkmcnt(0)
	s_barrier
	v_mfma_f32_16x16x32_bf16 v[60:63], v[152:155], v[168:171], v[60:63]
	v_mfma_f32_16x16x32_bf16 v[56:59], v[152:155], v[172:175], v[56:59]
	v_mfma_f32_16x16x32_bf16 v[52:55], v[152:155], v[176:179], v[52:55]
	v_mfma_f32_16x16x32_bf16 v[48:51], v[152:155], v[180:183], v[48:51]
	v_mfma_f32_16x16x32_bf16 v[44:47], v[156:159], v[168:171], v[44:47]
	v_mfma_f32_16x16x32_bf16 v[40:43], v[156:159], v[172:175], v[40:43]
	v_mfma_f32_16x16x32_bf16 v[36:39], v[156:159], v[176:179], v[36:39]
	v_mfma_f32_16x16x32_bf16 v[32:35], v[156:159], v[180:183], v[32:35]
	v_mfma_f32_16x16x32_bf16 v[28:31], v[160:163], v[168:171], v[28:31]
	v_mfma_f32_16x16x32_bf16 v[24:27], v[160:163], v[172:175], v[24:27]
	v_mfma_f32_16x16x32_bf16 v[20:23], v[160:163], v[176:179], v[20:23]
	v_mfma_f32_16x16x32_bf16 v[16:19], v[160:163], v[180:183], v[16:19]
	v_mfma_f32_16x16x32_bf16 v[12:15], v[164:167], v[168:171], v[12:15]
	v_mfma_f32_16x16x32_bf16 v[8:11], v[164:167], v[172:175], v[8:11]
	v_mfma_f32_16x16x32_bf16 v[4:7], v[164:167], v[176:179], v[4:7]
	v_mfma_f32_16x16x32_bf16 v[0:3], v[164:167], v[180:183], v[0:3]
	v_add_u32_e32 v100, 32, v85
	v_add_u32_e32 v96, v100, v84
	ds_read_b128 v[64:67], v96 offset:32768
	ds_read_b128 v[72:75], v96 offset:38912
	ds_read_b128 v[88:91], v96 offset:36864
	ds_read_b128 v[96:99], v96 offset:34816
	v_add_u32_e32 v82, 32, v86
	v_add_u32_e32 v92, v82, v84
	ds_read_b128 v[68:71], v92 offset:55296
	ds_read_b128 v[76:79], v92 offset:49152
	ds_read_b128 v[84:87], v92 offset:53248
	ds_read_b128 v[92:95], v92 offset:51200
	s_waitcnt lgkmcnt(0)
	v_mfma_f32_16x16x32_bf16 v[56:59], v[64:67], v[92:95], v[56:59]
	v_readlane_b32 s44, v252, 11
	v_readlane_b32 s45, v252, 12
	s_add_i32 s11, s11, s5
	v_mfma_f32_16x16x32_bf16 v[44:47], v[96:99], v[76:79], v[44:47]
	s_cmp_ge_u32 s11, s3
	v_readlane_b32 s46, v252, 13
	v_readlane_b32 s47, v252, 14
	v_mfma_f32_16x16x32_bf16 v[40:43], v[96:99], v[92:95], v[40:43]
	v_readlane_b32 s48, v252, 15
	v_readlane_b32 s49, v252, 16
	v_readlane_b32 s50, v252, 17
	v_mfma_f32_16x16x32_bf16 v[36:39], v[96:99], v[84:87], v[36:39]
	v_readlane_b32 s51, v252, 18
	v_mfma_f32_16x16x32_bf16 v[32:35], v[96:99], v[68:71], v[32:35]
	v_mfma_f32_16x16x32_bf16 v[96:99], v[88:91], v[92:95], v[24:27]
	v_mfma_f32_16x16x32_bf16 v[92:95], v[72:75], v[92:95], v[8:11]
	s_nop 2
	v_add_u32_e32 v8, v100, v83
	v_mfma_f32_16x16x32_bf16 v[60:63], v[64:67], v[76:79], v[60:63]
	v_add_u32_e32 v9, v82, v83
	v_mfma_f32_16x16x32_bf16 v[52:55], v[64:67], v[84:87], v[52:55]
	v_mfma_f32_16x16x32_bf16 v[48:51], v[64:67], v[68:71], v[48:51]
	v_mfma_f32_16x16x32_bf16 v[64:67], v[88:91], v[76:79], v[28:31]
	v_mfma_f32_16x16x32_bf16 v[20:23], v[88:91], v[84:87], v[20:23]
	v_mfma_f32_16x16x32_bf16 v[88:91], v[88:91], v[68:71], v[16:19]
	v_mfma_f32_16x16x32_bf16 v[76:79], v[72:75], v[76:79], v[12:15]
	v_mfma_f32_16x16x32_bf16 v[4:7], v[72:75], v[84:87], v[4:7]
	v_mfma_f32_16x16x32_bf16 v[68:71], v[72:75], v[68:71], v[0:3]
	ds_read_b128 v[72:75], v9 offset:49152
	ds_read_b128 v[12:15], v8 offset:34816
	ds_read_b128 v[100:103], v8 offset:36864
	ds_read_b128 v[0:3], v8 offset:32768
	ds_read_b128 v[108:111], v8 offset:38912
	ds_read_b128 v[104:107], v9 offset:53248
	ds_read_b128 v[112:115], v9 offset:55296
	ds_read_b128 v[82:85], v9 offset:51200
	s_waitcnt lgkmcnt(4)
	v_mfma_f32_16x16x32_bf16 v[60:63], v[0:3], v[72:75], v[60:63]
	s_waitcnt vmcnt(0)
	s_waitcnt lgkmcnt(0)
	s_barrier
	v_mfma_f32_16x16x32_bf16 v[24:27], v[0:3], v[104:107], v[52:55]
	v_mfma_f32_16x16x32_bf16 v[44:47], v[12:15], v[72:75], v[44:47]
	v_mfma_f32_16x16x32_bf16 v[28:31], v[12:15], v[104:107], v[36:39]
	v_mfma_f32_16x16x32_bf16 v[36:39], v[100:103], v[72:75], v[64:67]
	v_mfma_f32_16x16x32_bf16 v[16:19], v[100:103], v[104:107], v[20:23]
	v_mfma_f32_16x16x32_bf16 v[52:55], v[108:111], v[72:75], v[76:79]
	v_mul_f32_e32 v72, 0xbfb8aa3b, v61
	v_exp_f32_e32 v72, v72
	v_mul_f32_e32 v73, 0xbfb8aa3b, v63
	v_mfma_f32_16x16x32_bf16 v[20:23], v[108:111], v[104:107], v[4:7]
	v_exp_f32_e32 v73, v73
	s_nop 0
	v_add_f32_e32 v73, 1.0, v73
	v_mfma_f32_16x16x32_bf16 v[4:7], v[108:111], v[112:115], v[68:71]
	v_rcp_f32_e32 v73, v73
	s_nop 1
	v_mul_f32_e32 v71, 0xbfb8aa3b, v60
	v_exp_f32_e32 v71, v71
	v_lshrrev_b32_e32 v70, 1, v80
	v_and_b32_e32 v192, 24, v70
	v_mfma_f32_16x16x32_bf16 v[56:59], v[0:3], v[82:85], v[56:59]
	v_add_f32_e32 v70, 1.0, v71
	v_add_f32_e32 v71, 1.0, v72
	v_mul_f32_e32 v72, 0xbfb8aa3b, v62
	v_exp_f32_e32 v72, v72
	v_rcp_f32_e32 v70, v70
	v_rcp_f32_e32 v71, v71
	v_mfma_f32_16x16x32_bf16 v[40:43], v[12:15], v[82:85], v[40:43]
	v_add_f32_e32 v72, 1.0, v72
	v_rcp_f32_e32 v72, v72
	v_pk_mul_f32 v[60:61], v[60:61], v[70:71]
	v_mfma_f32_16x16x32_bf16 v[12:15], v[12:15], v[112:115], v[32:35]
	v_mul_f32_e64 v44, v44, v60
	v_mul_f32_e64 v45, v45, v61
	v_pk_mul_f32 v[60:61], v[62:63], v[72:73]
	v_cvt_pk_bf16_f32 v44, v44, v45
	v_mul_f32_e32 v45, 0xbfb8aa3b, v36
	v_pk_mul_f32 v[46:47], v[46:47], v[60:61]
	v_exp_f32_e32 v60, v45
	v_mul_f32_e32 v45, 0xbfb8aa3b, v37
	v_exp_f32_e32 v61, v45
	v_cvt_pk_bf16_f32 v45, v46, v47
	v_add_f32_e32 v46, 1.0, v60
	v_mul_f32_e32 v60, 0xbfb8aa3b, v38
	v_add_f32_e32 v47, 1.0, v61
	v_mul_f32_e32 v61, 0xbfb8aa3b, v39
	v_exp_f32_e32 v60, v60
	v_exp_f32_e32 v61, v61
	v_rcp_f32_e32 v46, v46
	v_rcp_f32_e32 v47, v47
	v_add_f32_e32 v60, 1.0, v60
	v_add_f32_e32 v61, 1.0, v61
	v_rcp_f32_e32 v60, v60
	v_rcp_f32_e32 v61, v61
	v_add_u32_e32 v32, s8, v81
	v_and_b32_e32 v33, 0x4f, v80
	v_ashrrev_i32_e32 v32, 1, v32
	v_or_b32_e32 v74, s12, v33
	v_ashrrev_i32_e32 v33, 31, v32
	v_mov_b64_e32 v[34:35], s[44:45]
	s_movk_i32 s8, 0x1600
	v_pk_mul_f32 v[36:37], v[36:37], v[46:47]
	v_pk_mul_f32 v[38:39], v[38:39], v[60:61]
	v_mad_i64_i32 v[68:69], s[16:17], v74, s8, v[34:35]
	v_lshlrev_b64 v[32:33], 1, v[32:33]
	v_pk_mul_f32 v[36:37], v[52:53], v[36:37]
	v_pk_mul_f32 v[38:39], v[54:55], v[38:39]
	v_lshl_add_u64 v[68:69], v[68:69], 0, v[32:33]
	v_cvt_pk_bf16_f32 v36, v36, v37
	v_cvt_pk_bf16_f32 v37, v38, v39
	v_mul_f32_e32 v38, 0xbfb8aa3b, v56
	v_mul_f32_e32 v39, 0xbfb8aa3b, v57
	v_lshl_add_u64 v[68:69], v[68:69], 0, v[192:193]
	v_exp_f32_e32 v38, v38
	v_exp_f32_e32 v39, v39
	global_store_dwordx2 v[68:69], v[44:45], off
	v_mul_f32_e32 v44, 0xbfb8aa3b, v58
	v_mul_f32_e32 v45, 0xbfb8aa3b, v59
	v_exp_f32_e32 v44, v44
	v_exp_f32_e32 v45, v45
	v_add_f32_e32 v38, 1.0, v38
	v_add_f32_e32 v39, 1.0, v39
	v_rcp_f32_e32 v38, v38
	v_rcp_f32_e32 v39, v39
	v_add_f32_e32 v44, 1.0, v44
	v_add_f32_e32 v45, 1.0, v45
	v_mfma_f32_16x16x32_bf16 v[8:11], v[0:3], v[112:115], v[48:51]
	v_rcp_f32_e32 v44, v44
	v_rcp_f32_e32 v45, v45
	v_pk_mul_f32 v[38:39], v[56:57], v[38:39]
	v_mfma_f32_16x16x32_bf16 v[48:51], v[100:103], v[82:85], v[96:99]
	v_mul_f32_e64 v38, v40, v38
	v_mul_f32_e64 v39, v41, v39
	v_pk_mul_f32 v[40:41], v[58:59], v[44:45]
	v_cvt_pk_bf16_f32 v38, v38, v39
	v_pk_mul_f32 v[40:41], v[42:43], v[40:41]
	global_store_dwordx2 v[68:69], v[36:37], off offset:32
	s_nop 1
	v_mul_f32_e32 v39, 0xbfb8aa3b, v48
	v_exp_f32_e32 v42, v39
	v_mul_f32_e32 v39, 0xbfb8aa3b, v49
	v_exp_f32_e32 v43, v39
	v_cvt_pk_bf16_f32 v39, v40, v41
	v_add_f32_e32 v40, 1.0, v42
	v_mul_f32_e32 v42, 0xbfb8aa3b, v50
	v_add_f32_e32 v41, 1.0, v43
	v_mul_f32_e32 v43, 0xbfb8aa3b, v51
	v_exp_f32_e32 v42, v42
	v_exp_f32_e32 v43, v43
	v_or_b32_e32 v36, 16, v74
	v_rcp_f32_e32 v40, v40
	v_add_f32_e32 v42, 1.0, v42
	v_add_f32_e32 v43, 1.0, v43
	v_rcp_f32_e32 v41, v41
	v_rcp_f32_e32 v42, v42
	v_rcp_f32_e32 v43, v43
	v_mfma_f32_16x16x32_bf16 v[64:67], v[108:111], v[82:85], v[92:95]
	v_mad_i64_i32 v[36:37], s[16:17], v36, s8, v[34:35]
	v_lshl_add_u64 v[36:37], v[36:37], 0, v[32:33]
	v_lshl_add_u64 v[36:37], v[36:37], 0, v[192:193]
	global_store_dwordx2 v[36:37], v[38:39], off
	v_pk_mul_f32 v[38:39], v[48:49], v[40:41]
	v_pk_mul_f32 v[40:41], v[50:51], v[42:43]
	s_nop 1
	v_pk_mul_f32 v[38:39], v[64:65], v[38:39]
	v_pk_mul_f32 v[40:41], v[66:67], v[40:41]
	v_cvt_pk_bf16_f32 v38, v38, v39
	v_cvt_pk_bf16_f32 v39, v40, v41
	global_store_dwordx2 v[36:37], v[38:39], off offset:32
	v_mul_f32_e32 v38, 0xbfb8aa3b, v24
	v_mul_f32_e32 v39, 0xbfb8aa3b, v25
	v_exp_f32_e32 v38, v38
	v_exp_f32_e32 v39, v39
	v_mul_f32_e32 v40, 0xbfb8aa3b, v26
	v_mul_f32_e32 v41, 0xbfb8aa3b, v27
	v_add_f32_e32 v38, 1.0, v38
	v_add_f32_e32 v39, 1.0, v39
	v_rcp_f32_e32 v38, v38
	v_rcp_f32_e32 v39, v39
	v_exp_f32_e32 v40, v40
	v_exp_f32_e32 v41, v41
	v_mfma_f32_16x16x32_bf16 v[0:3], v[100:103], v[112:115], v[88:91]
	v_mul_f32_e64 v24, v24, v38
	v_mul_f32_e64 v25, v25, v39
	v_add_f32_e32 v40, 1.0, v40
	v_add_f32_e32 v41, 1.0, v41
	v_pk_mul_f32 v[24:25], v[28:29], v[24:25]
	v_rcp_f32_e32 v40, v40
	v_rcp_f32_e32 v41, v41
	v_cvt_pk_bf16_f32 v24, v24, v25
	v_mul_f32_e32 v25, 0xbfb8aa3b, v16
	v_exp_f32_e32 v28, v25
	v_mul_f32_e32 v25, 0xbfb8aa3b, v17
	v_exp_f32_e32 v29, v25
	v_pk_mul_f32 v[26:27], v[26:27], v[40:41]
	v_or_b32_e32 v36, 32, v74
	v_pk_mul_f32 v[26:27], v[30:31], v[26:27]
	v_mad_i64_i32 v[36:37], s[16:17], v36, s8, v[34:35]
	v_cvt_pk_bf16_f32 v25, v26, v27
	v_add_f32_e32 v26, 1.0, v28
	v_add_f32_e32 v27, 1.0, v29
	v_mul_f32_e32 v28, 0xbfb8aa3b, v18
	v_mul_f32_e32 v29, 0xbfb8aa3b, v19
	v_exp_f32_e32 v28, v28
	v_exp_f32_e32 v29, v29
	v_rcp_f32_e32 v26, v26
	v_rcp_f32_e32 v27, v27
	v_add_f32_e32 v28, 1.0, v28
	v_add_f32_e32 v29, 1.0, v29
	v_rcp_f32_e32 v28, v28
	v_rcp_f32_e32 v29, v29
	v_pk_mul_f32 v[16:17], v[16:17], v[26:27]
	v_lshl_add_u64 v[36:37], v[36:37], 0, v[32:33]
	v_pk_mul_f32 v[16:17], v[20:21], v[16:17]
	v_pk_mul_f32 v[18:19], v[18:19], v[28:29]
	v_cvt_pk_bf16_f32 v16, v16, v17
	v_pk_mul_f32 v[18:19], v[22:23], v[18:19]
	v_mul_f32_e32 v20, 0xbfb8aa3b, v10
	v_cvt_pk_bf16_f32 v17, v18, v19
	v_mul_f32_e32 v18, 0xbfb8aa3b, v8
	v_mul_f32_e32 v19, 0xbfb8aa3b, v9
	v_exp_f32_e32 v18, v18
	v_exp_f32_e32 v19, v19
	v_mul_f32_e32 v21, 0xbfb8aa3b, v11
	v_exp_f32_e32 v20, v20
	v_add_f32_e32 v18, 1.0, v18
	v_add_f32_e32 v19, 1.0, v19
	v_rcp_f32_e32 v18, v18
	v_rcp_f32_e32 v19, v19
	v_exp_f32_e32 v21, v21
	v_add_f32_e32 v20, 1.0, v20
	v_rcp_f32_e32 v20, v20
	v_pk_mul_f32 v[8:9], v[8:9], v[18:19]
	v_add_f32_e32 v21, 1.0, v21
	v_pk_mul_f32 v[8:9], v[12:13], v[8:9]
	v_rcp_f32_e32 v21, v21
	v_cvt_pk_bf16_f32 v8, v8, v9
	v_mul_f32_e32 v9, 0xbfb8aa3b, v0
	v_exp_f32_e32 v12, v9
	v_mul_f32_e32 v9, 0xbfb8aa3b, v1
	v_exp_f32_e32 v13, v9
	v_pk_mul_f32 v[10:11], v[10:11], v[20:21]
	v_lshl_add_u64 v[36:37], v[36:37], 0, v[192:193]
	v_pk_mul_f32 v[10:11], v[14:15], v[10:11]
	global_store_dwordx2 v[36:37], v[16:17], off offset:32
	v_cvt_pk_bf16_f32 v9, v10, v11
	v_add_f32_e32 v10, 1.0, v12
	v_add_f32_e32 v11, 1.0, v13
	v_mul_f32_e32 v12, 0xbfb8aa3b, v2
	v_mul_f32_e32 v13, 0xbfb8aa3b, v3
	v_exp_f32_e32 v12, v12
	v_exp_f32_e32 v13, v13
	v_rcp_f32_e32 v10, v10
	v_rcp_f32_e32 v11, v11
	v_add_f32_e32 v12, 1.0, v12
	v_add_f32_e32 v13, 1.0, v13
	v_rcp_f32_e32 v12, v12
	v_rcp_f32_e32 v13, v13
	v_or_b32_e32 v16, 48, v74
	v_mad_i64_i32 v[16:17], s[16:17], v16, s8, v[34:35]
	v_pk_mul_f32 v[0:1], v[0:1], v[10:11]
	v_pk_mul_f32 v[2:3], v[2:3], v[12:13]
	v_lshl_add_u64 v[16:17], v[16:17], 0, v[32:33]
	v_pk_mul_f32 v[0:1], v[4:5], v[0:1]
	v_pk_mul_f32 v[2:3], v[6:7], v[2:3]
	v_lshl_add_u64 v[16:17], v[16:17], 0, v[192:193]
	v_cvt_pk_bf16_f32 v0, v0, v1
	v_cvt_pk_bf16_f32 v1, v2, v3
	global_store_dwordx2 v[36:37], v[24:25], off
	global_store_dwordx2 v[16:17], v[8:9], off
	global_store_dwordx2 v[16:17], v[0:1], off offset:32
	s_cbranch_scc0 .LBB0_62

.LBB0_79:
	s_nop 1
	v_sub_co_u32_e64 v0, s[10:11], s2, 64
	s_and_b64 s[10:11], s[10:11], exec
	v_readfirstlane_b32 s3, v0
	v_mov_b32_e32 v80, v220
	s_cselect_b32 s3, s2, s3
	s_cselect_b32 s10, 0, 8
	v_ashrrev_i32_e32 v16, 6, v80
	v_bfe_u32 v19, v80, 4, 2
	s_bfe_u32 s12, s3, 0x50003
	v_bfe_u32 v17, v80, 3, 3
	v_lshlrev_b32_e32 v18, 5, v16
	v_xor_b32_e32 v0, v19, v80
	s_add_i32 s16, s3, s10
	s_lshl_b32 s3, s12, 7
	v_or_b32_e32 v1, v18, v17
	v_lshlrev_b32_e32 v0, 3, v0
	v_add_u32_e32 v2, s3, v1
	v_and_b32_e32 v20, 56, v0
	v_or_b32_e32 v3, 8, v1
	s_lshl_b32 s17, s12, 13
	s_lshl_b32 s18, s16, 10
	v_lshl_or_b32 v192, v2, 10, v20
	v_lshrrev_b32_e32 v2, 1, v3
	s_sub_i32 s10, s18, s17
	v_xor_b32_e32 v2, v2, v80
	s_or_b32 s10, s10, s31
	v_lshlrev_b32_e32 v2, 3, v2
	v_add_u32_e32 v4, s3, v3
	v_and_b32_e32 v21, 56, v2
	v_add_u32_e32 v3, s10, v3
	v_lshl_or_b32 v2, v4, 10, v21
	v_lshl_or_b32 v4, v3, 10, v21
	v_or_b32_e32 v3, 16, v1
	v_add_u32_e32 v0, s10, v1
	v_add_u32_e32 v5, s3, v3
	v_add_u32_e32 v3, s10, v3
	v_or_b32_e32 v1, 24, v1
	v_lshl_or_b32 v8, v3, 10, v20
	v_lshrrev_b32_e32 v3, 1, v1
	v_xor_b32_e32 v3, v3, v80
	v_lshlrev_b32_e32 v3, 3, v3
	s_cmp_lg_u32 32, -1
	v_lshl_or_b32 v6, v5, 10, v20
	v_add_u32_e32 v5, s3, v1
	v_and_b32_e32 v22, 56, v3
	v_add_u32_e32 v1, s10, v1
	v_lshlrev_b32_e32 v23, 12, v16
	s_cselect_b32 s19, 32, 0
	v_ashrrev_i32_e32 v3, 1, v80
	v_lshl_or_b32 v12, v1, 10, v22
	v_add_u32_e32 v82, s19, v23
	v_and_b32_e32 v1, 15, v80
	v_and_b32_e32 v81, 0xffffffc0, v3
	s_add_i32 s40, s19, 0x4000
	v_or_b32_e32 v24, v81, v1
	v_lshlrev_b32_e32 v1, 7, v80
	v_add_u32_e32 v3, s40, v23
	v_readfirstlane_b32 s40, v82
	v_lshl_or_b32 v0, v0, 10, v20
	v_and_b32_e32 v83, 0x2780, v1
	v_lshl_add_u64 v[14:15], v[192:193], 1, s[0:1]
	s_mov_b32 m0, s40
	v_mov_b32_e32 v1, v193
	v_readfirstlane_b32 s40, v3
	global_load_lds_dwordx4 v[14:15], off
	v_lshl_add_u64 v[0:1], v[0:1], 1, s[74:75]
	s_mov_b32 m0, s40
	v_mov_b32_e32 v3, v193
	s_add_i32 s40, s19, 0x400
	global_load_lds_dwordx4 v[0:1], off
	v_lshl_add_u64 v[0:1], v[2:3], 1, s[0:1]
	v_add_u32_e32 v2, s40, v23
	v_lshl_or_b32 v10, v5, 10, v22
	v_readfirstlane_b32 s40, v2
	s_mov_b32 m0, s40
	s_add_i32 s40, s19, 0x4400
	v_add_u32_e32 v2, s40, v23
	global_load_lds_dwordx4 v[0:1], off
	v_readfirstlane_b32 s40, v2
	s_mov_b32 m0, s40
	s_add_i32 s40, s19, 0x800
	v_mov_b32_e32 v5, v193
	v_add_u32_e32 v2, s40, v23
	v_lshl_add_u64 v[0:1], v[4:5], 1, s[74:75]
	v_readfirstlane_b32 s40, v2
	global_load_lds_dwordx4 v[0:1], off
	s_mov_b32 m0, s40
	s_add_i32 s40, s19, 0x4800
	v_mov_b32_e32 v7, v193
	v_add_u32_e32 v2, s40, v23
	v_lshl_add_u64 v[0:1], v[6:7], 1, s[0:1]
	v_readfirstlane_b32 s40, v2
	global_load_lds_dwordx4 v[0:1], off
	s_mov_b32 m0, s40
	s_add_i32 s40, s19, 0xc00
	v_mov_b32_e32 v9, v193
	v_add_u32_e32 v2, s40, v23
	s_addk_i32 s19, 0x4c00
	v_lshl_add_u64 v[0:1], v[8:9], 1, s[74:75]
	v_mov_b32_e32 v11, v193
	v_readfirstlane_b32 s40, v2
	v_add_u32_e32 v2, s19, v23
	global_load_lds_dwordx4 v[0:1], off
	v_lshl_add_u64 v[0:1], v[10:11], 1, s[0:1]
	s_mov_b32 m0, s40
	v_mov_b32_e32 v13, v193
	v_readfirstlane_b32 s19, v2
	global_load_lds_dwordx4 v[0:1], off
	v_lshl_add_u64 v[0:1], v[12:13], 1, s[74:75]
	s_mov_b32 m0, s19
	s_or_b32 s18, s18, s31
	global_load_lds_dwordx4 v[0:1], off
	v_bfe_u32 v0, v80, 1, 3
	v_xor_b32_e32 v1, v19, v0
	v_bitop3_b32 v0, v19, v0, 4 bitop3:0x36
	v_lshlrev_b32_e32 v84, 4, v0
	v_or_b32_e32 v0, s3, v17
	v_add_u32_e32 v0, v0, v18
	v_lshl_or_b32 v192, v0, 10, v20
	v_lshlrev_b32_e32 v0, 15, v16
	v_lshlrev_b32_e32 v86, 4, v1
	v_lshlrev_b32_e32 v1, 10, v17
	v_lshl_add_u32 v2, s12, 17, v0
	v_or_b32_e32 v2, v2, v1
	v_lshl_add_u64 v[64:65], v[192:193], 1, s[28:29]
	v_or3_b32 v192, v2, v21, s33
	v_lshl_add_u64 v[66:67], v[192:193], 1, s[28:29]
	v_or3_b32 v192, v2, v20, s68
	v_lshl_add_u64 v[68:69], v[192:193], 1, s[28:29]
	v_or3_b32 v192, v2, v22, s67
	v_add3_u32 v2, s18, v17, v18
	s_lshl_b32 s16, s16, 20
	v_subrev_u32_e32 v2, s17, v2
	s_or_b32 s17, s58, s16
	v_lshl_add_u64 v[70:71], v[192:193], 1, s[28:29]
	v_lshl_or_b32 v192, v2, 10, v20
	v_add_u32_e32 v2, s17, v0
	v_add3_u32 v2, v2, v1, v21
	s_lshl_b32 s12, s12, 23
	s_or_b32 s17, s59, s16
	v_readlane_b32 s9, v254, 34
	v_lshl_add_u64 v[72:73], v[192:193], 1, s[56:57]
	v_subrev_u32_e32 v192, s12, v2
	v_add_u32_e32 v2, s17, v0
	s_or_b32 s16, s9, s16
	v_add3_u32 v2, v2, v1, v20
	v_add_u32_e32 v0, s16, v0
	s_waitcnt vmcnt(0)
	v_lshl_add_u64 v[74:75], v[192:193], 1, s[56:57]
	v_subrev_u32_e32 v192, s12, v2
	v_add3_u32 v0, v0, v1, v22
	v_lshl_add_u64 v[76:77], v[192:193], 1, s[56:57]
	v_subrev_u32_e32 v192, s12, v0
	v_mov_b32_e32 v0, 0
	s_mov_b32 s11, 0
	v_lshlrev_b32_e32 v85, 7, v24
	v_lshl_add_u64 v[78:79], v[192:193], 1, s[56:57]
	s_mov_b64 s[40:41], 0
	v_mov_b32_e32 v1, v0
	v_mov_b32_e32 v2, v0
	v_mov_b32_e32 v3, v0
	v_mov_b32_e32 v4, v0
	v_mov_b32_e32 v5, v0
	v_mov_b32_e32 v6, v0
	v_mov_b32_e32 v7, v0
	v_mov_b32_e32 v8, v0
	v_mov_b32_e32 v9, v0
	v_mov_b32_e32 v10, v0
	v_mov_b32_e32 v11, v0
	v_mov_b32_e32 v12, v0
	v_mov_b32_e32 v13, v0
	v_mov_b32_e32 v14, v0
	v_mov_b32_e32 v15, v0
	v_mov_b32_e32 v16, v0
	v_mov_b32_e32 v17, v0
	v_mov_b32_e32 v18, v0
	v_mov_b32_e32 v19, v0
	v_mov_b32_e32 v20, v0
	v_mov_b32_e32 v21, v0
	v_mov_b32_e32 v22, v0
	v_mov_b32_e32 v23, v0
	v_mov_b32_e32 v24, v0
	v_mov_b32_e32 v25, v0
	v_mov_b32_e32 v26, v0
	v_mov_b32_e32 v27, v0
	v_mov_b32_e32 v28, v0
	v_mov_b32_e32 v29, v0
	v_mov_b32_e32 v30, v0
	v_mov_b32_e32 v31, v0
	v_mov_b32_e32 v32, v0
	v_mov_b32_e32 v33, v0
	v_mov_b32_e32 v34, v0
	v_mov_b32_e32 v35, v0
	v_mov_b32_e32 v36, v0
	v_mov_b32_e32 v37, v0
	v_mov_b32_e32 v38, v0
	v_mov_b32_e32 v39, v0
	v_mov_b32_e32 v40, v0
	v_mov_b32_e32 v41, v0
	v_mov_b32_e32 v42, v0
	v_mov_b32_e32 v43, v0
	v_mov_b32_e32 v44, v0
	v_mov_b32_e32 v45, v0
	v_mov_b32_e32 v46, v0
	v_mov_b32_e32 v47, v0
	v_mov_b32_e32 v48, v0
	v_mov_b32_e32 v49, v0
	v_mov_b32_e32 v50, v0
	v_mov_b32_e32 v51, v0
	v_mov_b32_e32 v52, v0
	v_mov_b32_e32 v53, v0
	v_mov_b32_e32 v54, v0
	v_mov_b32_e32 v55, v0
	v_mov_b32_e32 v56, v0
	v_mov_b32_e32 v57, v0
	v_mov_b32_e32 v58, v0
	v_mov_b32_e32 v59, v0
	v_mov_b32_e32 v60, v0
	v_mov_b32_e32 v61, v0
	v_mov_b32_e32 v62, v0
	v_mov_b32_e32 v63, v0
	s_waitcnt vmcnt(0) lgkmcnt(0)
	s_barrier
	v_add_u32_e32 v134, 32, v85
	v_add_u32_e32 v135, 32, v83
	v_add_u32_e32 v132, v134, v86
	v_add_u32_e32 v133, v135, v86
	ds_read_b128 v[88:91], v132
	ds_read_b128 v[96:99], v132 offset:2048
	ds_read_b128 v[104:107], v132 offset:4096
	ds_read_b128 v[112:115], v132 offset:6144
	ds_read_b128 v[92:95], v133 offset:16384
	ds_read_b128 v[100:103], v133 offset:18432
	ds_read_b128 v[108:111], v133 offset:20480
	ds_read_b128 v[116:119], v133 offset:22528
	v_readfirstlane_b32 s98, v64
	v_readfirstlane_b32 s99, v65
	v_readfirstlane_b32 s100, v72
	v_readfirstlane_b32 s101, v73
	s_sub_u32 s98, s98, 0x80
	s_subb_u32 s99, s99, 0
	s_sub_u32 s100, s100, 0x80
	s_subb_u32 s101, s101, 0
	v_subrev_u32_e32 v64, s98, v64
	v_subrev_u32_e32 v66, s98, v66
	v_subrev_u32_e32 v68, s98, v68
	v_subrev_u32_e32 v70, s98, v70
	v_subrev_u32_e32 v72, s100, v72
	v_subrev_u32_e32 v74, s100, v74
	v_subrev_u32_e32 v76, s100, v76
	v_subrev_u32_e32 v78, s100, v78
	v_add_u32_e32 v128, 0x8000, v82
	s_nop 0
	v_readfirstlane_b32 s16, v128
	s_nop 1
	s_mov_b32 m0, s16
	s_nop 0
	global_load_lds_dwordx4 v64, s[98:99]
	s_add_i32 m0, s16, 0x4000
	s_nop 0
	global_load_lds_dwordx4 v72, s[100:101]
	s_add_i32 m0, s16, 0x400
	s_nop 0
	global_load_lds_dwordx4 v66, s[98:99]
	s_add_i32 m0, s16, 0x4400
	s_nop 0
	global_load_lds_dwordx4 v74, s[100:101]
	s_add_i32 m0, s16, 0x800
	s_nop 0
	global_load_lds_dwordx4 v68, s[98:99]
	s_add_i32 m0, s16, 0x4800
	s_nop 0
	global_load_lds_dwordx4 v76, s[100:101]
	s_add_i32 m0, s16, 0xc00
	s_nop 0
	global_load_lds_dwordx4 v70, s[98:99]
	s_add_i32 m0, s16, 0x4c00
	s_nop 0
	global_load_lds_dwordx4 v78, s[100:101]
	s_add_u32 s40, s40, 0x80
	s_addc_u32 s41, s41, 0
	s_add_u32 s98, s98, 0x80
	s_addc_u32 s99, s99, 0
	s_add_u32 s100, s100, 0x80
	s_addc_u32 s101, s101, 0
.Lg80_loop:
	s_and_b32 s12, s11, 0x8000
	s_xor_b32 s16, s12, 0x8000
	v_add_u32_e32 v132, v134, v84
	v_add_u32_e32 v133, v135, v84
	ds_read_b128 v[152:155], v132
	ds_read_b128 v[156:159], v132 offset:2048
	ds_read_b128 v[160:163], v132 offset:4096
	ds_read_b128 v[164:167], v132 offset:6144
	s_waitcnt lgkmcnt(4)
	v_mfma_f32_16x16x32_bf16 v[60:63], v[88:91], v[92:95], v[60:63]
	v_mfma_f32_16x16x32_bf16 v[56:59], v[88:91], v[100:103], v[56:59]
	v_mfma_f32_16x16x32_bf16 v[52:55], v[88:91], v[108:111], v[52:55]
	v_mfma_f32_16x16x32_bf16 v[48:51], v[88:91], v[116:119], v[48:51]
	ds_read_b128 v[168:171], v133 offset:16384
	ds_read_b128 v[172:175], v133 offset:18432
	ds_read_b128 v[176:179], v133 offset:20480
	ds_read_b128 v[180:183], v133 offset:22528
	v_mfma_f32_16x16x32_bf16 v[44:47], v[96:99], v[92:95], v[44:47]
	v_mfma_f32_16x16x32_bf16 v[40:43], v[96:99], v[100:103], v[40:43]
	v_mfma_f32_16x16x32_bf16 v[36:39], v[96:99], v[108:111], v[36:39]
	v_mfma_f32_16x16x32_bf16 v[32:35], v[96:99], v[116:119], v[32:35]
	v_mfma_f32_16x16x32_bf16 v[28:31], v[104:107], v[92:95], v[28:31]
	v_mfma_f32_16x16x32_bf16 v[24:27], v[104:107], v[100:103], v[24:27]
	v_mfma_f32_16x16x32_bf16 v[20:23], v[104:107], v[108:111], v[20:23]
	v_mfma_f32_16x16x32_bf16 v[16:19], v[104:107], v[116:119], v[16:19]
	v_mfma_f32_16x16x32_bf16 v[12:15], v[112:115], v[92:95], v[12:15]
	v_mfma_f32_16x16x32_bf16 v[8:11], v[112:115], v[100:103], v[8:11]
	v_mfma_f32_16x16x32_bf16 v[4:7], v[112:115], v[108:111], v[4:7]
	v_mfma_f32_16x16x32_bf16 v[0:3], v[112:115], v[116:119], v[0:3]
	s_waitcnt vmcnt(0) lgkmcnt(0)
	s_barrier
	v_add_u32_e32 v128, s12, v82
	s_add_i32 s12, s16, 32
	v_add_u32_e32 v134, s12, v85
	v_add_u32_e32 v135, s12, v83
	v_add_u32_e32 v132, v134, v86
	v_add_u32_e32 v133, v135, v86
	ds_read_b128 v[88:91], v132
	ds_read_b128 v[96:99], v132 offset:2048
	ds_read_b128 v[104:107], v132 offset:4096
	ds_read_b128 v[112:115], v132 offset:6144
	ds_read_b128 v[92:95], v133 offset:16384
	ds_read_b128 v[100:103], v133 offset:18432
	ds_read_b128 v[108:111], v133 offset:20480
	ds_read_b128 v[116:119], v133 offset:22528
	v_readfirstlane_b32 s16, v128
	v_mfma_f32_16x16x32_bf16 v[60:63], v[152:155], v[168:171], v[60:63]
	s_mov_b32 m0, s16
	s_nop 0
	global_load_lds_dwordx4 v64, s[98:99]
	v_mfma_f32_16x16x32_bf16 v[56:59], v[152:155], v[172:175], v[56:59]
	v_mfma_f32_16x16x32_bf16 v[52:55], v[152:155], v[176:179], v[52:55]
	s_add_i32 m0, s16, 0x4000
	s_nop 0
	global_load_lds_dwordx4 v72, s[100:101]
	v_mfma_f32_16x16x32_bf16 v[48:51], v[152:155], v[180:183], v[48:51]
	v_mfma_f32_16x16x32_bf16 v[44:47], v[156:159], v[168:171], v[44:47]
	s_add_i32 m0, s16, 0x400
	s_nop 0
	global_load_lds_dwordx4 v66, s[98:99]
	v_mfma_f32_16x16x32_bf16 v[40:43], v[156:159], v[172:175], v[40:43]
	v_mfma_f32_16x16x32_bf16 v[36:39], v[156:159], v[176:179], v[36:39]
	s_add_i32 m0, s16, 0x4400
	s_nop 0
	global_load_lds_dwordx4 v74, s[100:101]
	v_mfma_f32_16x16x32_bf16 v[32:35], v[156:159], v[180:183], v[32:35]
	v_mfma_f32_16x16x32_bf16 v[28:31], v[160:163], v[168:171], v[28:31]
	s_add_i32 m0, s16, 0x800
	s_nop 0
	global_load_lds_dwordx4 v68, s[98:99]
	v_mfma_f32_16x16x32_bf16 v[24:27], v[160:163], v[172:175], v[24:27]
	v_mfma_f32_16x16x32_bf16 v[20:23], v[160:163], v[176:179], v[20:23]
	s_add_i32 m0, s16, 0x4800
	s_nop 0
	global_load_lds_dwordx4 v76, s[100:101]
	v_mfma_f32_16x16x32_bf16 v[16:19], v[160:163], v[180:183], v[16:19]
	v_mfma_f32_16x16x32_bf16 v[12:15], v[164:167], v[168:171], v[12:15]
	s_add_i32 m0, s16, 0xc00
	s_nop 0
	global_load_lds_dwordx4 v70, s[98:99]
	v_mfma_f32_16x16x32_bf16 v[8:11], v[164:167], v[172:175], v[8:11]
	v_mfma_f32_16x16x32_bf16 v[4:7], v[164:167], v[176:179], v[4:7]
	s_add_i32 m0, s16, 0x4c00
	s_nop 0
	global_load_lds_dwordx4 v78, s[100:101]
	v_mfma_f32_16x16x32_bf16 v[0:3], v[164:167], v[180:183], v[0:3]
	s_add_i32 s11, s11, 0x8000
	s_add_u32 s40, s40, 0x80
	s_addc_u32 s41, s41, 0
	s_add_u32 s98, s98, 0x80
	s_addc_u32 s99, s99, 0
	s_add_u32 s100, s100, 0x80
	s_addc_u32 s101, s101, 0
	s_cmpk_lg_i32 s40, 0x780
	s_cbranch_scc1 .Lg80_loop
	s_and_b32 s12, s11, 0x8000
	s_xor_b32 s16, s12, 0x8000
	v_add_u32_e32 v132, v134, v84
	v_add_u32_e32 v133, v135, v84
	ds_read_b128 v[152:155], v132
	ds_read_b128 v[156:159], v132 offset:2048
	ds_read_b128 v[160:163], v132 offset:4096
	ds_read_b128 v[164:167], v132 offset:6144
	s_waitcnt lgkmcnt(4)
	v_mfma_f32_16x16x32_bf16 v[60:63], v[88:91], v[92:95], v[60:63]
	v_mfma_f32_16x16x32_bf16 v[56:59], v[88:91], v[100:103], v[56:59]
	v_mfma_f32_16x16x32_bf16 v[52:55], v[88:91], v[108:111], v[52:55]
	v_mfma_f32_16x16x32_bf16 v[48:51], v[88:91], v[116:119], v[48:51]
	ds_read_b128 v[168:171], v133 offset:16384
	ds_read_b128 v[172:175], v133 offset:18432
	ds_read_b128 v[176:179], v133 offset:20480
	ds_read_b128 v[180:183], v133 offset:22528
	v_mfma_f32_16x16x32_bf16 v[44:47], v[96:99], v[92:95], v[44:47]
	v_mfma_f32_16x16x32_bf16 v[40:43], v[96:99], v[100:103], v[40:43]
	v_mfma_f32_16x16x32_bf16 v[36:39], v[96:99], v[108:111], v[36:39]
	v_mfma_f32_16x16x32_bf16 v[32:35], v[96:99], v[116:119], v[32:35]
	v_mfma_f32_16x16x32_bf16 v[28:31], v[104:107], v[92:95], v[28:31]
	v_mfma_f32_16x16x32_bf16 v[24:27], v[104:107], v[100:103], v[24:27]
	v_mfma_f32_16x16x32_bf16 v[20:23], v[104:107], v[108:111], v[20:23]
	v_mfma_f32_16x16x32_bf16 v[16:19], v[104:107], v[116:119], v[16:19]
	v_mfma_f32_16x16x32_bf16 v[12:15], v[112:115], v[92:95], v[12:15]
	v_mfma_f32_16x16x32_bf16 v[8:11], v[112:115], v[100:103], v[8:11]
	v_mfma_f32_16x16x32_bf16 v[4:7], v[112:115], v[108:111], v[4:7]
	v_mfma_f32_16x16x32_bf16 v[0:3], v[112:115], v[116:119], v[0:3]
	s_waitcnt vmcnt(0) lgkmcnt(0)
	s_barrier
	v_mfma_f32_16x16x32_bf16 v[60:63], v[152:155], v[168:171], v[60:63]
	v_mfma_f32_16x16x32_bf16 v[56:59], v[152:155], v[172:175], v[56:59]
	v_mfma_f32_16x16x32_bf16 v[52:55], v[152:155], v[176:179], v[52:55]
	v_mfma_f32_16x16x32_bf16 v[48:51], v[152:155], v[180:183], v[48:51]
	v_mfma_f32_16x16x32_bf16 v[44:47], v[156:159], v[168:171], v[44:47]
	v_mfma_f32_16x16x32_bf16 v[40:43], v[156:159], v[172:175], v[40:43]
	v_mfma_f32_16x16x32_bf16 v[36:39], v[156:159], v[176:179], v[36:39]
	v_mfma_f32_16x16x32_bf16 v[32:35], v[156:159], v[180:183], v[32:35]
	v_mfma_f32_16x16x32_bf16 v[28:31], v[160:163], v[168:171], v[28:31]
	v_mfma_f32_16x16x32_bf16 v[24:27], v[160:163], v[172:175], v[24:27]
	v_mfma_f32_16x16x32_bf16 v[20:23], v[160:163], v[176:179], v[20:23]
	v_mfma_f32_16x16x32_bf16 v[16:19], v[160:163], v[180:183], v[16:19]
	v_mfma_f32_16x16x32_bf16 v[12:15], v[164:167], v[168:171], v[12:15]
	v_mfma_f32_16x16x32_bf16 v[8:11], v[164:167], v[172:175], v[8:11]
	v_mfma_f32_16x16x32_bf16 v[4:7], v[164:167], v[176:179], v[4:7]
	v_mfma_f32_16x16x32_bf16 v[0:3], v[164:167], v[180:183], v[0:3]
	v_add_u32_e32 v82, 32, v85
	v_add_u32_e32 v83, 32, v83
	v_add_u32_e32 v85, v82, v86
	ds_read_b128 v[64:67], v85 offset:32768
	v_add_u32_e32 v98, v83, v86
	ds_read_b128 v[72:75], v85 offset:34816
	ds_read_b128 v[86:89], v85 offset:36864
	ds_read_b128 v[94:97], v85 offset:38912
	ds_read_b128 v[90:93], v98 offset:53248
	ds_read_b128 v[68:71], v98 offset:49152
	ds_read_b128 v[76:79], v98 offset:51200
	ds_read_b128 v[98:101], v98 offset:55296
	s_waitcnt lgkmcnt(3)
	v_mfma_f32_16x16x32_bf16 v[52:55], v[64:67], v[90:93], v[52:55]
	s_add_i32 s2, s2, s8
	s_cmpk_gt_u32 s2, 0x7f
	v_mfma_f32_16x16x32_bf16 v[36:39], v[72:75], v[90:93], v[36:39]
	v_mfma_f32_16x16x32_bf16 v[20:23], v[86:89], v[90:93], v[20:23]
	v_mfma_f32_16x16x32_bf16 v[4:7], v[94:97], v[90:93], v[4:7]
	v_add_u32_e32 v90, v82, v84
	s_waitcnt lgkmcnt(2)
	v_mfma_f32_16x16x32_bf16 v[60:63], v[64:67], v[68:71], v[60:63]
	s_waitcnt lgkmcnt(1)
	v_mfma_f32_16x16x32_bf16 v[56:59], v[64:67], v[76:79], v[56:59]
	s_waitcnt lgkmcnt(0)
	v_mfma_f32_16x16x32_bf16 v[48:51], v[64:67], v[98:101], v[48:51]
	v_mfma_f32_16x16x32_bf16 v[44:47], v[72:75], v[68:71], v[44:47]
	v_mfma_f32_16x16x32_bf16 v[40:43], v[72:75], v[76:79], v[40:43]
	v_mfma_f32_16x16x32_bf16 v[32:35], v[72:75], v[98:101], v[32:35]
	v_mfma_f32_16x16x32_bf16 v[28:31], v[86:89], v[68:71], v[28:31]
	v_mfma_f32_16x16x32_bf16 v[24:27], v[86:89], v[76:79], v[24:27]
	v_mfma_f32_16x16x32_bf16 v[16:19], v[86:89], v[98:101], v[16:19]
	v_mfma_f32_16x16x32_bf16 v[12:15], v[94:97], v[68:71], v[12:15]
	v_mfma_f32_16x16x32_bf16 v[8:11], v[94:97], v[76:79], v[8:11]
	v_mfma_f32_16x16x32_bf16 v[0:3], v[94:97], v[98:101], v[0:3]
	ds_read_b128 v[64:67], v90 offset:32768
	v_add_u32_e32 v94, v83, v84
	ds_read_b128 v[72:75], v90 offset:34816
	ds_read_b128 v[82:85], v90 offset:36864
	ds_read_b128 v[90:93], v90 offset:38912
	ds_read_b128 v[68:71], v94 offset:49152
	ds_read_b128 v[76:79], v94 offset:51200
	ds_read_b128 v[86:89], v94 offset:53248
	ds_read_b128 v[94:97], v94 offset:55296
	s_waitcnt lgkmcnt(3)
	v_mfma_f32_16x16x32_bf16 v[60:63], v[64:67], v[68:71], v[60:63]
	s_waitcnt vmcnt(0)
	s_waitcnt lgkmcnt(0)
	s_barrier
	v_mfma_f32_16x16x32_bf16 v[56:59], v[64:67], v[76:79], v[56:59]
	s_nop 4
	v_cvt_pk_bf16_f32 v60, v60, v61
	v_cvt_pk_bf16_f32 v61, v62, v63
	v_mfma_f32_16x16x32_bf16 v[52:55], v[64:67], v[86:89], v[52:55]
	v_mfma_f32_16x16x32_bf16 v[48:51], v[64:67], v[94:97], v[48:51]
	v_and_b32_e32 v65, 0x4f, v80
	v_or_b32_e32 v66, s10, v65
	v_add_u32_e32 v64, s3, v81
	v_mfma_f32_16x16x32_bf16 v[12:15], v[90:93], v[68:71], v[12:15]
	v_ashrrev_i32_e32 v67, 31, v66
	v_ashrrev_i32_e32 v65, 31, v64
	v_lshlrev_b64 v[64:65], 1, v[64:65]
	v_mfma_f32_16x16x32_bf16 v[44:47], v[72:75], v[68:71], v[44:47]
	v_mfma_f32_16x16x32_bf16 v[28:31], v[82:85], v[68:71], v[28:31]
	v_lshlrev_b64 v[68:69], 11, v[66:67]
	v_lshl_add_u64 v[68:69], s[72:73], 0, v[68:69]
	v_lshrrev_b32_e32 v67, 1, v80
	v_lshl_add_u64 v[68:69], v[68:69], 0, v[64:65]
	v_and_b32_e32 v192, 24, v67
	v_lshl_add_u64 v[68:69], v[68:69], 0, v[192:193]
	v_cvt_pk_bf16_f32 v12, v12, v13
	v_cvt_pk_bf16_f32 v13, v14, v15
	global_store_dwordx2 v[68:69], v[12:13], off offset:96
	v_or_b32_e32 v12, 16, v66
	v_mfma_f32_16x16x32_bf16 v[8:11], v[90:93], v[76:79], v[8:11]
	v_ashrrev_i32_e32 v13, 31, v12
	v_lshlrev_b64 v[12:13], 11, v[12:13]
	v_lshl_add_u64 v[12:13], s[72:73], 0, v[12:13]
	v_lshl_add_u64 v[12:13], v[12:13], 0, v[64:65]
	v_lshl_add_u64 v[12:13], v[12:13], 0, v[192:193]
	s_nop 2
	v_cvt_pk_bf16_f32 v8, v8, v9
	v_cvt_pk_bf16_f32 v9, v10, v11
	global_store_dwordx2 v[12:13], v[8:9], off offset:96
	v_or_b32_e32 v8, 32, v66
	v_mfma_f32_16x16x32_bf16 v[4:7], v[90:93], v[86:89], v[4:7]
	v_ashrrev_i32_e32 v9, 31, v8
	v_lshlrev_b64 v[8:9], 11, v[8:9]
	v_lshl_add_u64 v[8:9], s[72:73], 0, v[8:9]
	v_lshl_add_u64 v[8:9], v[8:9], 0, v[64:65]
	v_lshl_add_u64 v[8:9], v[8:9], 0, v[192:193]
	s_nop 2
	v_cvt_pk_bf16_f32 v4, v4, v5
	v_cvt_pk_bf16_f32 v5, v6, v7
	global_store_dwordx2 v[8:9], v[4:5], off offset:96
	v_or_b32_e32 v4, 48, v66
	v_ashrrev_i32_e32 v5, 31, v4
	v_mfma_f32_16x16x32_bf16 v[40:43], v[72:75], v[76:79], v[40:43]
	v_lshlrev_b64 v[4:5], 11, v[4:5]
	v_lshl_add_u64 v[4:5], s[72:73], 0, v[4:5]
	v_lshl_add_u64 v[4:5], v[4:5], 0, v[64:65]
	v_mfma_f32_16x16x32_bf16 v[36:39], v[72:75], v[86:89], v[36:39]
	v_cvt_pk_bf16_f32 v14, v56, v57
	v_cvt_pk_bf16_f32 v15, v58, v59
	v_cvt_pk_bf16_f32 v10, v52, v53
	v_mfma_f32_16x16x32_bf16 v[32:35], v[72:75], v[94:97], v[32:35]
	v_cvt_pk_bf16_f32 v11, v54, v55
	v_lshl_add_u64 v[4:5], v[4:5], 0, v[192:193]
	v_cvt_pk_bf16_f32 v6, v48, v49
	v_mfma_f32_16x16x32_bf16 v[24:27], v[82:85], v[76:79], v[24:27]
	v_cvt_pk_bf16_f32 v7, v50, v51
	global_store_dwordx2 v[12:13], v[14:15], off
	v_cvt_pk_bf16_f32 v14, v40, v41
	v_mfma_f32_16x16x32_bf16 v[20:23], v[82:85], v[86:89], v[20:23]
	v_cvt_pk_bf16_f32 v15, v42, v43
	global_store_dwordx2 v[8:9], v[10:11], off
	v_cvt_pk_bf16_f32 v10, v36, v37
	v_mfma_f32_16x16x32_bf16 v[16:19], v[82:85], v[94:97], v[16:19]
	v_cvt_pk_bf16_f32 v11, v38, v39
	global_store_dwordx2 v[4:5], v[6:7], off
	v_cvt_pk_bf16_f32 v6, v32, v33
	v_mfma_f32_16x16x32_bf16 v[0:3], v[90:93], v[94:97], v[0:3]
	v_cvt_pk_bf16_f32 v7, v34, v35
	v_cvt_pk_bf16_f32 v44, v44, v45
	v_cvt_pk_bf16_f32 v45, v46, v47
	v_cvt_pk_bf16_f32 v28, v28, v29
	v_cvt_pk_bf16_f32 v29, v30, v31
	global_store_dwordx2 v[12:13], v[14:15], off offset:32
	v_cvt_pk_bf16_f32 v14, v24, v25
	v_cvt_pk_bf16_f32 v15, v26, v27
	global_store_dwordx2 v[8:9], v[10:11], off offset:32
	v_cvt_pk_bf16_f32 v10, v20, v21
	v_cvt_pk_bf16_f32 v11, v22, v23
	global_store_dwordx2 v[4:5], v[6:7], off offset:32
	v_cvt_pk_bf16_f32 v6, v16, v17
	v_cvt_pk_bf16_f32 v7, v18, v19
	v_cvt_pk_bf16_f32 v0, v0, v1
	v_cvt_pk_bf16_f32 v1, v2, v3
	global_store_dwordx2 v[68:69], v[60:61], off
	global_store_dwordx2 v[68:69], v[44:45], off offset:32
	global_store_dwordx2 v[68:69], v[28:29], off offset:64
	global_store_dwordx2 v[12:13], v[14:15], off offset:64
	global_store_dwordx2 v[8:9], v[10:11], off offset:64
	global_store_dwordx2 v[4:5], v[6:7], off offset:64
	global_store_dwordx2 v[4:5], v[0:1], off offset:96
	s_cbranch_scc0 .LBB0_79

.LBB0_253:
	s_min_i32 s2, s3, 8
	s_lshl_b32 s12, s2, 4
	s_mov_b32 s10, s8
	s_add_i32 s1, s1, 8
	s_add_i32 s3, s3, -8
	s_add_i32 s0, s0, -8
	s_sub_i32 s8, s8, s12
	s_cmp_ge_i32 s10, s12
	s_cbranch_scc1 .LBB0_253
	s_lshl_b32 s3, s2, 3
	s_abs_i32 s8, s3
	v_cvt_f32_u32_e32 v0, s8
	s_sub_i32 s16, 0, s8
	s_abs_i32 s13, s10
	s_xor_b32 s12, s10, s3
	v_rcp_iflag_f32_e32 v0, v0
	s_ashr_i32 s12, s12, 31
	v_mov_b32_e32 v81, v220
	v_mul_f32_e32 v0, 0x4f7ffffe, v0
	v_cvt_u32_f32_e32 v0, v0
	v_ashrrev_i32_e32 v16, 6, v81
	v_bfe_u32 v80, v81, 4, 2
	v_bfe_u32 v17, v81, 3, 3
	v_readfirstlane_b32 s17, v0
	s_mul_i32 s16, s16, s17
	s_mul_hi_u32 s16, s17, s16
	s_add_i32 s17, s17, s16
	s_mul_hi_u32 s16, s13, s17
	s_mul_i32 s17, s16, s8
	s_sub_i32 s13, s13, s17
	s_add_i32 s18, s16, 1
	s_sub_i32 s17, s13, s8
	s_cmp_ge_u32 s13, s8
	s_cselect_b32 s16, s18, s16
	s_cselect_b32 s13, s17, s13
	s_add_i32 s17, s16, 1
	s_cmp_ge_u32 s13, s8
	s_cselect_b32 s13, s17, s16
	s_abs_i32 s17, s2
	v_cvt_f32_u32_e32 v0, s17
	s_xor_b32 s16, s13, s12
	s_sub_i32 s13, 0, s17
	s_sub_i32 s18, s16, s12
	v_rcp_iflag_f32_e32 v0, v0
	s_mul_i32 s3, s18, s3
	s_sub_i32 s3, s10, s3
	s_abs_i32 s28, s3
	v_mul_f32_e32 v0, 0x4f7ffffe, v0
	v_cvt_u32_f32_e32 v0, v0
	s_xor_b32 s19, s3, s2
	s_ashr_i32 s19, s19, 31
	v_lshlrev_b32_e32 v18, 5, v16
	v_readfirstlane_b32 s29, v0
	s_mul_i32 s13, s13, s29
	s_mul_hi_u32 s13, s29, s13
	s_add_i32 s29, s29, s13
	s_mul_hi_u32 s13, s28, s29
	s_mul_i32 s29, s13, s17
	s_sub_i32 s28, s28, s29
	s_add_i32 s38, s13, 1
	s_sub_i32 s29, s28, s17
	s_cmp_ge_u32 s28, s17
	s_cselect_b32 s13, s38, s13
	s_cselect_b32 s28, s29, s28
	s_add_i32 s29, s13, 1
	s_cmp_ge_u32 s28, s17
	s_cselect_b32 s13, s29, s13
	s_xor_b32 s17, s13, s19
	s_sub_i32 s13, s17, s19
	s_mul_i32 s2, s13, s2
	s_add_i32 s3, s3, s1
	s_sub_i32 s3, s3, s2
	s_lshl_b32 s2, s18, 10
	s_lshl_b32 s13, s13, 7
	v_xor_b32_e32 v0, v80, v81
	s_add_i32 s2, s13, s2
	v_or_b32_e32 v1, v18, v17
	v_lshlrev_b32_e32 v0, 3, v0
	v_add_u32_e32 v2, s2, v1
	v_and_b32_e32 v19, 56, v0
	v_or_b32_e32 v3, 8, v1
	v_lshl_or_b32 v192, v2, 10, v19
	v_lshrrev_b32_e32 v2, 1, v3
	s_lshl_b32 s13, s3, 10
	v_readlane_b32 s3, v252, 39
	v_xor_b32_e32 v2, v2, v81
	s_or_b32 s3, s13, s3
	v_lshlrev_b32_e32 v2, 3, v2
	v_add_u32_e32 v4, s2, v3
	v_and_b32_e32 v20, 56, v2
	v_add_u32_e32 v3, s3, v3
	v_lshl_or_b32 v2, v4, 10, v20
	v_lshl_or_b32 v4, v3, 10, v20
	v_or_b32_e32 v3, 16, v1
	v_add_u32_e32 v0, s3, v1
	s_waitcnt lgkmcnt(0)
	v_add_u32_e32 v5, s2, v3
	v_add_u32_e32 v3, s3, v3
	v_or_b32_e32 v1, 24, v1
	v_lshl_or_b32 v8, v3, 10, v19
	v_lshrrev_b32_e32 v3, 1, v1
	v_xor_b32_e32 v3, v3, v81
	s_cmp_lg_u32 32, -1
	v_lshlrev_b32_e32 v3, 3, v3
	v_lshlrev_b32_e32 v22, 12, v16
	s_cselect_b32 s18, 32, 0
	v_lshl_or_b32 v6, v5, 10, v19
	v_add_u32_e32 v5, s2, v1
	v_and_b32_e32 v21, 56, v3
	v_add_u32_e32 v1, s3, v1
	v_add_u32_e32 v85, s18, v22
	s_add_i32 s28, s18, 0x4000
	v_lshl_or_b32 v12, v1, 10, v21
	v_ashrrev_i32_e32 v1, 1, v81
	v_add_u32_e32 v3, s28, v22
	v_readfirstlane_b32 s28, v85
	v_lshl_or_b32 v0, v0, 10, v19
	v_and_b32_e32 v83, 0xffffffc0, v1
	v_lshl_add_u64 v[14:15], v[192:193], 1, s[96:97]
	s_mov_b32 m0, s28
	v_mov_b32_e32 v1, v193
	v_readfirstlane_b32 s28, v3
	global_load_lds_dwordx4 v[14:15], off
	v_lshl_add_u64 v[0:1], v[0:1], 1, s[74:75]
	s_mov_b32 m0, s28
	v_mov_b32_e32 v3, v193
	s_add_i32 s28, s18, 0x400
	global_load_lds_dwordx4 v[0:1], off
	v_lshl_add_u64 v[0:1], v[2:3], 1, s[96:97]
	v_add_u32_e32 v2, s28, v22
	v_lshl_or_b32 v10, v5, 10, v21
	v_readfirstlane_b32 s28, v2
	s_mov_b32 m0, s28
	s_add_i32 s28, s18, 0x4400
	v_add_u32_e32 v2, s28, v22
	global_load_lds_dwordx4 v[0:1], off
	v_readfirstlane_b32 s28, v2
	s_mov_b32 m0, s28
	s_add_i32 s28, s18, 0x800
	v_mov_b32_e32 v5, v193
	v_add_u32_e32 v2, s28, v22
	v_lshl_add_u64 v[0:1], v[4:5], 1, s[74:75]
	v_readfirstlane_b32 s28, v2
	global_load_lds_dwordx4 v[0:1], off
	s_mov_b32 m0, s28
	s_add_i32 s28, s18, 0x4800
	v_mov_b32_e32 v7, v193
	v_add_u32_e32 v2, s28, v22
	v_lshl_add_u64 v[0:1], v[6:7], 1, s[96:97]
	v_readfirstlane_b32 s28, v2
	global_load_lds_dwordx4 v[0:1], off
	s_mov_b32 m0, s28
	s_add_i32 s28, s18, 0xc00
	v_mov_b32_e32 v9, v193
	v_add_u32_e32 v2, s28, v22
	s_addk_i32 s18, 0x4c00
	v_lshl_add_u64 v[0:1], v[8:9], 1, s[74:75]
	v_mov_b32_e32 v11, v193
	v_readfirstlane_b32 s28, v2
	v_add_u32_e32 v2, s18, v22
	global_load_lds_dwordx4 v[0:1], off
	v_lshl_add_u64 v[0:1], v[10:11], 1, s[96:97]
	s_mov_b32 m0, s28
	v_mov_b32_e32 v13, v193
	v_readfirstlane_b32 s18, v2
	global_load_lds_dwordx4 v[0:1], off
	v_lshl_add_u64 v[0:1], v[12:13], 1, s[74:75]
	s_mov_b32 m0, s18
	s_lshl_b32 s18, s16, 10
	global_load_lds_dwordx4 v[0:1], off
	v_bfe_u32 v0, v81, 1, 3
	s_lshl_b32 s28, s17, 7
	v_xor_b32_e32 v1, v80, v0
	v_bitop3_b32 v0, v80, v0, 4 bitop3:0x36
	s_add_i32 s28, s28, s18
	v_lshlrev_b32_e32 v86, 4, v0
	v_or_b32_e32 v0, s28, v17
	v_add_u32_e32 v0, v0, v18
	s_lshl_b32 s18, s19, 7
	v_subrev_u32_e32 v0, s18, v0
	s_lshl_b32 s18, s12, 10
	v_subrev_u32_e32 v0, s18, v0
	s_lshl_b32 s18, s16, 20
	s_lshl_b32 s28, s17, 17
	v_lshl_or_b32 v192, v0, 10, v19
	v_lshlrev_b32_e32 v0, 15, v16
	s_add_i32 s18, s18, s28
	v_lshlrev_b32_e32 v87, 4, v1
	v_lshlrev_b32_e32 v1, 10, v17
	v_add_u32_e32 v2, s18, v0
	v_or_b32_e32 v2, v2, v1
	s_add_i32 s1, s10, s1
	s_lshl_b32 s10, s12, 3
	v_or3_b32 v3, v2, v20, s33
	s_lshl_b32 s18, s19, 17
	s_add_i32 s19, s19, s10
	v_subrev_u32_e32 v3, s18, v3
	s_lshl_b32 s28, s12, 20
	s_sub_i32 s10, s19, s17
	s_lshl_b32 s12, s16, 3
	v_lshl_add_u64 v[64:65], v[192:193], 1, s[68:69]
	v_subrev_u32_e32 v192, s28, v3
	v_or3_b32 v3, v2, v19, s30
	s_sub_i32 s10, s10, s12
	s_min_i32 s0, s0, 8
	v_subrev_u32_e32 v3, s18, v3
	v_or3_b32 v2, v2, v21, s67
	s_mul_i32 s10, s10, s0
	v_lshl_add_u64 v[66:67], v[192:193], 1, s[68:69]
	v_subrev_u32_e32 v192, s28, v3
	v_subrev_u32_e32 v2, s18, v2
	s_add_i32 s1, s1, s10
	v_lshl_add_u64 v[68:69], v[192:193], 1, s[68:69]
	v_subrev_u32_e32 v192, s28, v2
	v_add_u32_e32 v2, s31, v17
	s_lshl_b32 s0, s1, 10
	v_add3_u32 v2, v2, v18, s0
	v_lshl_add_u64 v[70:71], v[192:193], 1, s[68:69]
	v_lshl_or_b32 v192, v2, 10, v19
	v_add3_u32 v2, s58, v0, v1
	s_lshl_b32 s0, s1, 20
	v_lshl_add_u64 v[72:73], v[192:193], 1, s[56:57]
	v_add3_u32 v192, v2, v20, s0
	v_add3_u32 v2, s59, v0, v1
	v_readlane_b32 s1, v254, 34
	v_and_b32_e32 v84, 15, v81
	s_waitcnt vmcnt(0)
	v_lshl_add_u64 v[74:75], v[192:193], 1, s[56:57]
	v_add3_u32 v192, v2, v19, s0
	v_add3_u32 v0, s1, v0, v1
	v_or_b32_e32 v23, v83, v84
	v_lshlrev_b32_e32 v24, 7, v81
	v_lshl_add_u64 v[76:77], v[192:193], 1, s[56:57]
	v_add3_u32 v192, v0, v21, s0
	v_mov_b32_e32 v56, 0
	s_mov_b32 s8, 0
	v_and_b32_e32 v82, 63, v81
	v_lshlrev_b32_e32 v88, 7, v23
	v_and_b32_e32 v89, 0x2780, v24
	v_lshl_add_u64 v[78:79], v[192:193], 1, s[56:57]
	s_mov_b64 s[0:1], 0
	v_mov_b32_e32 v57, v56
	v_mov_b32_e32 v58, v56
	v_mov_b32_e32 v59, v56
	v_mov_b32_e32 v60, v56
	v_mov_b32_e32 v61, v56
	v_mov_b32_e32 v62, v56
	v_mov_b32_e32 v63, v56
	v_mov_b32_e32 v0, v56
	v_mov_b32_e32 v1, v56
	v_mov_b32_e32 v2, v56
	v_mov_b32_e32 v3, v56
	v_mov_b32_e32 v4, v56
	v_mov_b32_e32 v5, v56
	v_mov_b32_e32 v6, v56
	v_mov_b32_e32 v7, v56
	v_mov_b32_e32 v8, v56
	v_mov_b32_e32 v9, v56
	v_mov_b32_e32 v10, v56
	v_mov_b32_e32 v11, v56
	v_mov_b32_e32 v12, v56
	v_mov_b32_e32 v13, v56
	v_mov_b32_e32 v14, v56
	v_mov_b32_e32 v15, v56
	v_mov_b32_e32 v16, v56
	v_mov_b32_e32 v17, v56
	v_mov_b32_e32 v18, v56
	v_mov_b32_e32 v19, v56
	v_mov_b32_e32 v20, v56
	v_mov_b32_e32 v21, v56
	v_mov_b32_e32 v22, v56
	v_mov_b32_e32 v23, v56
	v_mov_b32_e32 v24, v56
	v_mov_b32_e32 v25, v56
	v_mov_b32_e32 v26, v56
	v_mov_b32_e32 v27, v56
	v_mov_b32_e32 v28, v56
	v_mov_b32_e32 v29, v56
	v_mov_b32_e32 v30, v56
	v_mov_b32_e32 v31, v56
	v_mov_b32_e32 v32, v56
	v_mov_b32_e32 v33, v56
	v_mov_b32_e32 v34, v56
	v_mov_b32_e32 v35, v56
	v_mov_b32_e32 v36, v56
	v_mov_b32_e32 v37, v56
	v_mov_b32_e32 v38, v56
	v_mov_b32_e32 v39, v56
	v_mov_b32_e32 v40, v56
	v_mov_b32_e32 v41, v56
	v_mov_b32_e32 v42, v56
	v_mov_b32_e32 v43, v56
	v_mov_b32_e32 v44, v56
	v_mov_b32_e32 v45, v56
	v_mov_b32_e32 v46, v56
	v_mov_b32_e32 v47, v56
	v_mov_b32_e32 v48, v56
	v_mov_b32_e32 v49, v56
	v_mov_b32_e32 v50, v56
	v_mov_b32_e32 v51, v56
	v_mov_b32_e32 v52, v56
	v_mov_b32_e32 v53, v56
	v_mov_b32_e32 v54, v56
	v_mov_b32_e32 v55, v56
	s_waitcnt vmcnt(0) lgkmcnt(0)
	s_barrier
	v_add_u32_e32 v134, 32, v88
	v_add_u32_e32 v135, 32, v89
	v_add_u32_e32 v132, v134, v87
	v_add_u32_e32 v133, v135, v87
	ds_read_b128 v[90:93], v132
	ds_read_b128 v[98:101], v132 offset:2048
	ds_read_b128 v[106:109], v132 offset:4096
	ds_read_b128 v[114:117], v132 offset:6144
	ds_read_b128 v[94:97], v133 offset:16384
	ds_read_b128 v[102:105], v133 offset:18432
	ds_read_b128 v[110:113], v133 offset:20480
	ds_read_b128 v[118:121], v133 offset:22528
	v_readfirstlane_b32 s98, v64
	v_readfirstlane_b32 s99, v65
	v_readfirstlane_b32 s100, v72
	v_readfirstlane_b32 s101, v73
	s_sub_u32 s98, s98, 0x80
	s_subb_u32 s99, s99, 0
	s_sub_u32 s100, s100, 0x80
	s_subb_u32 s101, s101, 0
	v_subrev_u32_e32 v64, s98, v64
	v_subrev_u32_e32 v66, s98, v66
	v_subrev_u32_e32 v68, s98, v68
	v_subrev_u32_e32 v70, s98, v70
	v_subrev_u32_e32 v72, s100, v72
	v_subrev_u32_e32 v74, s100, v74
	v_subrev_u32_e32 v76, s100, v76
	v_subrev_u32_e32 v78, s100, v78
	v_add_u32_e32 v128, 0x8000, v85
	s_nop 0
	v_readfirstlane_b32 s12, v128
	s_nop 1
	s_mov_b32 m0, s12
	s_nop 0
	global_load_lds_dwordx4 v64, s[98:99]
	s_add_i32 m0, s12, 0x4000
	s_nop 0
	global_load_lds_dwordx4 v72, s[100:101]
	s_add_i32 m0, s12, 0x400
	s_nop 0
	global_load_lds_dwordx4 v66, s[98:99]
	s_add_i32 m0, s12, 0x4400
	s_nop 0
	global_load_lds_dwordx4 v74, s[100:101]
	s_add_i32 m0, s12, 0x800
	s_nop 0
	global_load_lds_dwordx4 v68, s[98:99]
	s_add_i32 m0, s12, 0x4800
	s_nop 0
	global_load_lds_dwordx4 v76, s[100:101]
	s_add_i32 m0, s12, 0xc00
	s_nop 0
	global_load_lds_dwordx4 v70, s[98:99]
	s_add_i32 m0, s12, 0x4c00
	s_nop 0
	global_load_lds_dwordx4 v78, s[100:101]
	s_add_u32 s0, s0, 0x80
	s_addc_u32 s1, s1, 0
	s_add_u32 s98, s98, 0x80
	s_addc_u32 s99, s99, 0
	s_add_u32 s100, s100, 0x80
	s_addc_u32 s101, s101, 0
.Lg255_loop:
	s_and_b32 s10, s8, 0x8000
	s_xor_b32 s12, s10, 0x8000
	v_add_u32_e32 v132, v134, v86
	v_add_u32_e32 v133, v135, v86
	ds_read_b128 v[152:155], v132
	ds_read_b128 v[156:159], v132 offset:2048
	ds_read_b128 v[160:163], v132 offset:4096
	ds_read_b128 v[164:167], v132 offset:6144
	s_waitcnt lgkmcnt(4)
	v_mfma_f32_16x16x32_bf16 v[52:55], v[90:93], v[94:97], v[52:55]
	v_mfma_f32_16x16x32_bf16 v[48:51], v[90:93], v[102:105], v[48:51]
	v_mfma_f32_16x16x32_bf16 v[44:47], v[90:93], v[110:113], v[44:47]
	v_mfma_f32_16x16x32_bf16 v[40:43], v[90:93], v[118:121], v[40:43]
	ds_read_b128 v[168:171], v133 offset:16384
	ds_read_b128 v[172:175], v133 offset:18432
	ds_read_b128 v[176:179], v133 offset:20480
	ds_read_b128 v[180:183], v133 offset:22528
	v_mfma_f32_16x16x32_bf16 v[36:39], v[98:101], v[94:97], v[36:39]
	v_mfma_f32_16x16x32_bf16 v[32:35], v[98:101], v[102:105], v[32:35]
	v_mfma_f32_16x16x32_bf16 v[28:31], v[98:101], v[110:113], v[28:31]
	v_mfma_f32_16x16x32_bf16 v[24:27], v[98:101], v[118:121], v[24:27]
	v_mfma_f32_16x16x32_bf16 v[20:23], v[106:109], v[94:97], v[20:23]
	v_mfma_f32_16x16x32_bf16 v[16:19], v[106:109], v[102:105], v[16:19]
	v_mfma_f32_16x16x32_bf16 v[12:15], v[106:109], v[110:113], v[12:15]
	v_mfma_f32_16x16x32_bf16 v[8:11], v[106:109], v[118:121], v[8:11]
	v_mfma_f32_16x16x32_bf16 v[4:7], v[114:117], v[94:97], v[4:7]
	v_mfma_f32_16x16x32_bf16 v[0:3], v[114:117], v[102:105], v[0:3]
	v_mfma_f32_16x16x32_bf16 v[60:63], v[114:117], v[110:113], v[60:63]
	v_mfma_f32_16x16x32_bf16 v[56:59], v[114:117], v[118:121], v[56:59]
	s_waitcnt vmcnt(0) lgkmcnt(0)
	s_barrier
	v_add_u32_e32 v128, s10, v85
	s_add_i32 s10, s12, 32
	v_add_u32_e32 v134, s10, v88
	v_add_u32_e32 v135, s10, v89
	v_add_u32_e32 v132, v134, v87
	v_add_u32_e32 v133, v135, v87
	ds_read_b128 v[90:93], v132
	ds_read_b128 v[98:101], v132 offset:2048
	ds_read_b128 v[106:109], v132 offset:4096
	ds_read_b128 v[114:117], v132 offset:6144
	ds_read_b128 v[94:97], v133 offset:16384
	ds_read_b128 v[102:105], v133 offset:18432
	ds_read_b128 v[110:113], v133 offset:20480
	ds_read_b128 v[118:121], v133 offset:22528
	v_readfirstlane_b32 s12, v128
	v_mfma_f32_16x16x32_bf16 v[52:55], v[152:155], v[168:171], v[52:55]
	s_mov_b32 m0, s12
	s_nop 0
	global_load_lds_dwordx4 v64, s[98:99]
	v_mfma_f32_16x16x32_bf16 v[48:51], v[152:155], v[172:175], v[48:51]
	v_mfma_f32_16x16x32_bf16 v[44:47], v[152:155], v[176:179], v[44:47]
	s_add_i32 m0, s12, 0x4000
	s_nop 0
	global_load_lds_dwordx4 v72, s[100:101]
	v_mfma_f32_16x16x32_bf16 v[40:43], v[152:155], v[180:183], v[40:43]
	v_mfma_f32_16x16x32_bf16 v[36:39], v[156:159], v[168:171], v[36:39]
	s_add_i32 m0, s12, 0x400
	s_nop 0
	global_load_lds_dwordx4 v66, s[98:99]
	v_mfma_f32_16x16x32_bf16 v[32:35], v[156:159], v[172:175], v[32:35]
	v_mfma_f32_16x16x32_bf16 v[28:31], v[156:159], v[176:179], v[28:31]
	s_add_i32 m0, s12, 0x4400
	s_nop 0
	global_load_lds_dwordx4 v74, s[100:101]
	v_mfma_f32_16x16x32_bf16 v[24:27], v[156:159], v[180:183], v[24:27]
	v_mfma_f32_16x16x32_bf16 v[20:23], v[160:163], v[168:171], v[20:23]
	s_add_i32 m0, s12, 0x800
	s_nop 0
	global_load_lds_dwordx4 v68, s[98:99]
	v_mfma_f32_16x16x32_bf16 v[16:19], v[160:163], v[172:175], v[16:19]
	v_mfma_f32_16x16x32_bf16 v[12:15], v[160:163], v[176:179], v[12:15]
	s_add_i32 m0, s12, 0x4800
	s_nop 0
	global_load_lds_dwordx4 v76, s[100:101]
	v_mfma_f32_16x16x32_bf16 v[8:11], v[160:163], v[180:183], v[8:11]
	v_mfma_f32_16x16x32_bf16 v[4:7], v[164:167], v[168:171], v[4:7]
	s_add_i32 m0, s12, 0xc00
	s_nop 0
	global_load_lds_dwordx4 v70, s[98:99]
	v_mfma_f32_16x16x32_bf16 v[0:3], v[164:167], v[172:175], v[0:3]
	v_mfma_f32_16x16x32_bf16 v[60:63], v[164:167], v[176:179], v[60:63]
	s_add_i32 m0, s12, 0x4c00
	s_nop 0
	global_load_lds_dwordx4 v78, s[100:101]
	v_mfma_f32_16x16x32_bf16 v[56:59], v[164:167], v[180:183], v[56:59]
	s_add_i32 s8, s8, 0x8000
	s_add_u32 s0, s0, 0x80
	s_addc_u32 s1, s1, 0
	s_add_u32 s98, s98, 0x80
	s_addc_u32 s99, s99, 0
	s_add_u32 s100, s100, 0x80
	s_addc_u32 s101, s101, 0
	s_cmpk_lg_i32 s0, 0x780
	s_cbranch_scc1 .Lg255_loop
	s_and_b32 s10, s8, 0x8000
	s_xor_b32 s12, s10, 0x8000
	v_add_u32_e32 v132, v134, v86
	v_add_u32_e32 v133, v135, v86
	ds_read_b128 v[152:155], v132
	ds_read_b128 v[156:159], v132 offset:2048
	ds_read_b128 v[160:163], v132 offset:4096
	ds_read_b128 v[164:167], v132 offset:6144
	s_waitcnt lgkmcnt(4)
	v_mfma_f32_16x16x32_bf16 v[52:55], v[90:93], v[94:97], v[52:55]
	v_mfma_f32_16x16x32_bf16 v[48:51], v[90:93], v[102:105], v[48:51]
	v_mfma_f32_16x16x32_bf16 v[44:47], v[90:93], v[110:113], v[44:47]
	v_mfma_f32_16x16x32_bf16 v[40:43], v[90:93], v[118:121], v[40:43]
	ds_read_b128 v[168:171], v133 offset:16384
	ds_read_b128 v[172:175], v133 offset:18432
	ds_read_b128 v[176:179], v133 offset:20480
	ds_read_b128 v[180:183], v133 offset:22528
	v_mfma_f32_16x16x32_bf16 v[36:39], v[98:101], v[94:97], v[36:39]
	v_mfma_f32_16x16x32_bf16 v[32:35], v[98:101], v[102:105], v[32:35]
	v_mfma_f32_16x16x32_bf16 v[28:31], v[98:101], v[110:113], v[28:31]
	v_mfma_f32_16x16x32_bf16 v[24:27], v[98:101], v[118:121], v[24:27]
	v_mfma_f32_16x16x32_bf16 v[20:23], v[106:109], v[94:97], v[20:23]
	v_mfma_f32_16x16x32_bf16 v[16:19], v[106:109], v[102:105], v[16:19]
	v_mfma_f32_16x16x32_bf16 v[12:15], v[106:109], v[110:113], v[12:15]
	v_mfma_f32_16x16x32_bf16 v[8:11], v[106:109], v[118:121], v[8:11]
	v_mfma_f32_16x16x32_bf16 v[4:7], v[114:117], v[94:97], v[4:7]
	v_mfma_f32_16x16x32_bf16 v[0:3], v[114:117], v[102:105], v[0:3]
	v_mfma_f32_16x16x32_bf16 v[60:63], v[114:117], v[110:113], v[60:63]
	v_mfma_f32_16x16x32_bf16 v[56:59], v[114:117], v[118:121], v[56:59]
	s_waitcnt vmcnt(0) lgkmcnt(0)
	s_barrier
	v_mfma_f32_16x16x32_bf16 v[52:55], v[152:155], v[168:171], v[52:55]
	v_mfma_f32_16x16x32_bf16 v[48:51], v[152:155], v[172:175], v[48:51]
	v_mfma_f32_16x16x32_bf16 v[44:47], v[152:155], v[176:179], v[44:47]
	v_mfma_f32_16x16x32_bf16 v[40:43], v[152:155], v[180:183], v[40:43]
	v_mfma_f32_16x16x32_bf16 v[36:39], v[156:159], v[168:171], v[36:39]
	v_mfma_f32_16x16x32_bf16 v[32:35], v[156:159], v[172:175], v[32:35]
	v_mfma_f32_16x16x32_bf16 v[28:31], v[156:159], v[176:179], v[28:31]
	v_mfma_f32_16x16x32_bf16 v[24:27], v[156:159], v[180:183], v[24:27]
	v_mfma_f32_16x16x32_bf16 v[20:23], v[160:163], v[168:171], v[20:23]
	v_mfma_f32_16x16x32_bf16 v[16:19], v[160:163], v[172:175], v[16:19]
	v_mfma_f32_16x16x32_bf16 v[12:15], v[160:163], v[176:179], v[12:15]
	v_mfma_f32_16x16x32_bf16 v[8:11], v[160:163], v[180:183], v[8:11]
	v_mfma_f32_16x16x32_bf16 v[4:7], v[164:167], v[168:171], v[4:7]
	v_mfma_f32_16x16x32_bf16 v[0:3], v[164:167], v[172:175], v[0:3]
	v_mfma_f32_16x16x32_bf16 v[60:63], v[164:167], v[176:179], v[60:63]
	v_mfma_f32_16x16x32_bf16 v[56:59], v[164:167], v[180:183], v[56:59]
	v_add_u32_e32 v112, 32, v88
	v_add_u32_e32 v100, v112, v87
	ds_read_b128 v[92:95], v100 offset:36864
	ds_read_b128 v[64:67], v100 offset:32768
	ds_read_b128 v[72:75], v100 offset:38912
	ds_read_b128 v[100:103], v100 offset:34816
	v_add_u32_e32 v85, 32, v89
	v_add_u32_e32 v87, v85, v87
	ds_read_b128 v[88:91], v87 offset:53248
	ds_read_b128 v[68:71], v87 offset:55296
	ds_read_b128 v[76:79], v87 offset:49152
	ds_read_b128 v[96:99], v87 offset:51200
	s_waitcnt lgkmcnt(3)
	v_mfma_f32_16x16x32_bf16 v[108:111], v[92:95], v[88:91], v[12:15]
	v_and_or_b32 v81, v81, 64, s3
	s_movk_i32 s0, 0x3fff
	s_nop 0
	v_add_u32_e32 v12, v112, v86
	s_waitcnt lgkmcnt(1)
	v_mfma_f32_16x16x32_bf16 v[52:55], v[64:67], v[76:79], v[52:55]
	v_add_u32_e32 v13, v85, v86
	s_waitcnt lgkmcnt(0)
	v_mfma_f32_16x16x32_bf16 v[48:51], v[64:67], v[96:99], v[48:51]
	v_mfma_f32_16x16x32_bf16 v[104:107], v[64:67], v[88:91], v[44:47]
	v_mfma_f32_16x16x32_bf16 v[40:43], v[64:67], v[68:71], v[40:43]
	v_mfma_f32_16x16x32_bf16 v[36:39], v[100:103], v[76:79], v[36:39]
	v_mfma_f32_16x16x32_bf16 v[32:35], v[100:103], v[96:99], v[32:35]
	v_mfma_f32_16x16x32_bf16 v[64:67], v[100:103], v[88:91], v[28:31]
	v_mfma_f32_16x16x32_bf16 v[24:27], v[100:103], v[68:71], v[24:27]
	v_mfma_f32_16x16x32_bf16 v[100:103], v[92:95], v[76:79], v[20:23]
	v_mfma_f32_16x16x32_bf16 v[16:19], v[92:95], v[96:99], v[16:19]
	v_mfma_f32_16x16x32_bf16 v[8:11], v[92:95], v[68:71], v[8:11]
	v_mfma_f32_16x16x32_bf16 v[76:79], v[72:75], v[76:79], v[4:7]
	v_mfma_f32_16x16x32_bf16 v[0:3], v[72:75], v[96:99], v[0:3]
	v_mfma_f32_16x16x32_bf16 v[88:91], v[72:75], v[88:91], v[60:63]
	v_mfma_f32_16x16x32_bf16 v[68:71], v[72:75], v[68:71], v[56:59]
	ds_read_b128 v[4:7], v12 offset:32768
	ds_read_b128 v[96:99], v12 offset:36864
	ds_read_b128 v[116:119], v12 offset:38912
	ds_read_b128 v[56:59], v12 offset:34816
	ds_read_b128 v[72:75], v13 offset:49152
	ds_read_b128 v[92:95], v13 offset:51200
	ds_read_b128 v[112:115], v13 offset:53248
	ds_read_b128 v[120:123], v13 offset:55296
	s_waitcnt lgkmcnt(3)
	v_mfma_f32_16x16x32_bf16 v[60:63], v[4:7], v[72:75], v[52:55]
	s_waitcnt vmcnt(0)
	s_waitcnt lgkmcnt(0)
	s_barrier
	v_mfma_f32_16x16x32_bf16 v[44:47], v[4:7], v[92:95], v[48:51]
	v_mfma_f32_16x16x32_bf16 v[28:31], v[4:7], v[112:115], v[104:107]
	v_mfma_f32_16x16x32_bf16 v[12:15], v[4:7], v[120:123], v[40:43]
	v_mfma_f32_16x16x32_bf16 v[52:55], v[56:59], v[72:75], v[36:39]
	v_mfma_f32_16x16x32_bf16 v[36:39], v[56:59], v[92:95], v[32:35]
	v_mfma_f32_16x16x32_bf16 v[20:23], v[56:59], v[112:115], v[64:67]
	v_mfma_f32_16x16x32_bf16 v[4:7], v[56:59], v[120:123], v[24:27]
	s_nop 1
	v_or_b32_e32 v66, v81, v84
	v_cmp_lt_i32_e32 vcc, s0, v66
	v_mfma_f32_16x16x32_bf16 v[56:59], v[96:99], v[72:75], v[100:103]
	v_mfma_f32_16x16x32_bf16 v[40:43], v[96:99], v[92:95], v[16:19]
	v_mfma_f32_16x16x32_bf16 v[24:27], v[96:99], v[112:115], v[108:111]
	v_mfma_f32_16x16x32_bf16 v[8:11], v[96:99], v[120:123], v[8:11]
	v_mfma_f32_16x16x32_bf16 v[48:51], v[116:119], v[72:75], v[76:79]
	v_mfma_f32_16x16x32_bf16 v[32:35], v[116:119], v[92:95], v[0:3]
	v_mfma_f32_16x16x32_bf16 v[16:19], v[116:119], v[112:115], v[88:91]
	v_mfma_f32_16x16x32_bf16 v[0:3], v[116:119], v[120:123], v[68:71]
	s_and_saveexec_b64 s[0:1], vcc
	s_xor_b64 s[0:1], exec, s[0:1]
	s_addk_i32 s3, 0xc000
	s_lshr_b32 s3, s3, 8
	v_and_b32_e32 v64, 0xcf, v66
	v_or_b32_e32 v192, 0x2000, v64
	v_mov_b32_e32 v65, s3
	s_andn2_saveexec_b64 s[0:1], s[0:1]
	s_ashr_i32 s3, s13, 13
	v_and_b32_e32 v192, 0x1fcf, v66
	v_mov_b32_e32 v65, s3
	s_or_b64 exec, exec, s[0:1]
	v_add_u32_e32 v64, s2, v83
	s_movk_i32 s0, 0x17f
	v_cmp_lt_i32_e64 s[48:49], s0, v64
	s_movk_i32 s0, 0x480
	s_movk_i32 s2, 0x780
	v_subrev_co_u32_e32 v67, vcc, 0x380, v64
	v_cmp_gt_u32_e64 s[42:43], s0, v64
	s_movk_i32 s0, 0x47f
	v_cmp_eq_u32_e64 s[2:3], s2, v64
	s_xor_b64 s[88:89], vcc, -1
	v_cmp_lt_u32_e32 vcc, s0, v64
	v_and_b32_e32 v68, 0x7fffff80, v64
	s_movk_i32 s0, 0x700
	v_writelane_b32 v255, s2, 20
	v_cmp_ne_u32_e64 s[0:1], s0, v68
	s_and_b64 s[14:15], vcc, s[0:1]
	v_writelane_b32 v255, s3, 21
	s_movk_i32 s2, 0x680
	v_subrev_co_u32_e32 v68, vcc, 0x700, v64
	v_cmp_gt_u32_e64 s[44:45], s2, v64
	s_movk_i32 s2, 0x280
	v_mov_b32_e32 v69, 0xfffff980
	v_mov_b32_e32 v70, 0xfffffb80
	v_ashrrev_i32_e32 v78, 6, v68
	v_lshrrev_b32_e32 v79, 6, v67
	v_mov_b32_e32 v67, 0xfffffd80
	v_mov_b32_e32 v68, 0xfffffe80
	v_cmp_gt_u32_e64 s[40:41], s2, v64
	v_cndmask_b32_e64 v69, v69, v70, s[44:45]
	v_add_u32_e32 v69, v69, v64
	v_cndmask_b32_e64 v67, v67, v68, s[40:41]
	v_add_u32_e32 v67, v67, v64
	s_xor_b64 s[0:1], vcc, -1
	v_lshlrev_b32_e32 v76, 3, v80
	v_lshlrev_b32_e32 v74, 2, v80
	v_lshrrev_b32_e32 v75, 6, v69
	v_ashrrev_i32_e32 v77, 5, v67
	v_cmp_gt_u32_e64 s[38:39], 16, v82
	s_and_saveexec_b64 s[2:3], s[48:49]
	s_xor_b64 s[90:91], exec, s[2:3]
	s_cbranch_execz .LBB0_286
	v_cmp_gt_u32_e64 s[50:51], s33, v192
	s_and_saveexec_b64 s[2:3], s[88:89]
	s_xor_b64 s[92:93], exec, s[2:3]
	s_cbranch_execz .LBB0_279
	s_and_saveexec_b64 s[2:3], s[14:15]
	s_xor_b64 s[94:95], exec, s[2:3]
	s_cbranch_execz .LBB0_276
	s_and_saveexec_b64 s[2:3], s[0:1]
	s_xor_b64 s[46:47], exec, s[2:3]
	s_cbranch_execz .LBB0_269
	s_mov_b64 vcc, exec
	v_readlane_b32 s2, v255, 20
	v_readlane_b32 s3, v255, 21
	s_and_b64 s[2:3], vcc, s[2:3]
	s_mov_b64 exec, s[2:3]
	s_cbranch_execz .LBB0_268
	s_and_saveexec_b64 s[2:3], s[50:51]
	s_cbranch_execz .LBB0_267
	v_readlane_b32 s16, v254, 9
	v_lshlrev_b32_e32 v48, 7, v192
	v_mov_b32_e32 v49, v193
	v_readlane_b32 s24, v254, 17
	v_readlane_b32 s25, v254, 18
	v_lshlrev_b32_e32 v50, 2, v76
	v_mov_b32_e32 v51, v193
	v_lshl_add_u64 v[48:49], s[24:25], 0, v[48:49]
	v_lshl_add_u64 v[56:57], v[48:49], 0, v[50:51]
	global_load_dwordx4 v[48:51], v[56:57], off
	s_nop 0
	global_load_dwordx4 v[56:59], v[56:57], off offset:16
	v_readlane_b32 s30, v254, 23
	v_readlane_b32 s31, v254, 24
	s_movk_i32 s30, 0x4000
	s_mov_b32 s31, s9
	v_readlane_b32 s17, v254, 10
	v_readlane_b32 s18, v254, 11
	v_readlane_b32 s19, v254, 12
	v_readlane_b32 s20, v254, 13
	v_readlane_b32 s21, v254, 14
	v_readlane_b32 s22, v254, 15
	v_readlane_b32 s23, v254, 16
	v_readlane_b32 s26, v254, 19
	v_readlane_b32 s27, v254, 20
	v_readlane_b32 s28, v254, 21
	v_readlane_b32 s29, v254, 22
	s_waitcnt vmcnt(1)
	v_mov_b32_e32 v68, v49
	s_waitcnt vmcnt(0)
	v_mov_b32_e32 v70, v57
	v_mov_b32_e32 v71, v59
	v_mov_b32_e32 v69, v51
	v_mov_b32_e32 v57, v58
	v_mov_b32_e32 v49, v50
	v_pk_mul_f32 v[50:51], v[54:55], v[70:71]
	v_pk_mul_f32 v[58:59], v[52:53], v[68:69]
	v_pk_mul_f32 v[52:53], v[52:53], v[48:49]
	v_pk_mul_f32 v[54:55], v[54:55], v[56:57]
	v_pk_fma_f32 v[50:51], v[62:63], v[56:57], v[50:51] neg_lo:[0,0,1] neg_hi:[0,0,1]
	v_pk_fma_f32 v[48:49], v[60:61], v[48:49], v[58:59] neg_lo:[0,0,1] neg_hi:[0,0,1]
	v_pk_fma_f32 v[54:55], v[62:63], v[70:71], v[54:55]
	v_pk_fma_f32 v[52:53], v[60:61], v[68:69], v[52:53]
	v_mov_b64_e32 v[62:63], v[50:51]
	v_mov_b64_e32 v[60:61], v[48:49]
